# v6 + LDS-DMA issue blocks trimmed in the 9 bf16 K-loops (no m0 save/restore, s_nop 0)
# speedup vs baseline: 1.0039x; 1.0039x over previous
.LBB0_156:
	v_add_u32_e32 v139, 0x10000, v137
	ds_read_b128 v[140:143], v139
	ds_read_b128 v[144:147], v139 offset:1024
	ds_read_b128 v[148:151], v139 offset:2048
	ds_read_b128 v[152:155], v139 offset:3072
	v_add_u32_e32 v139, 0x14000, v137
	ds_read_b128 v[156:159], v139
	ds_read_b128 v[160:163], v139 offset:1024
	ds_read_b128 v[164:167], v139 offset:2048
	ds_read_b128 v[168:171], v139 offset:3072
	s_add_u32 s0, s52, 0x100
	s_addc_u32 s1, s53, 0
	s_cmp_eq_u32 s89, 12
	s_cselect_b32 s34, s15, s0
	s_cselect_b32 s35, s14, s1
	s_cselect_b32 s56, s41, s87
	s_cselect_b32 s57, s11, s88
	s_add_u32 s54, s34, 0x80
	s_addc_u32 s55, s35, 0
	ds_read_b128 v[172:175], v138
	ds_read_b128 v[176:179], v138 offset:1024
	ds_read_b128 v[180:183], v138 offset:2048
	ds_read_b128 v[184:187], v138 offset:3072
	ds_read_b128 v[188:191], v138 offset:4096
	ds_read_b128 v[192:195], v138 offset:5120
	ds_read_b128 v[196:199], v138 offset:6144
	ds_read_b128 v[200:203], v138 offset:7168
	s_add_u32 s90, s52, 0x40080
	s_addc_u32 s91, s53, 0
	s_mov_b32 m0, s83
	s_nop 0
	global_load_lds_dwordx4 v1, s[90:91]
	s_add_u32 s52, s52, 0x60080
	s_addc_u32 s53, s53, 0
	s_add_i32 s12, s51, 0xe000
	s_mov_b32 m0, s12
	s_nop 0
	global_load_lds_dwordx4 v1, s[52:53]
	s_waitcnt vmcnt(8)
	s_waitcnt lgkmcnt(0)
	s_barrier
	s_waitcnt lgkmcnt(7)
	v_mfma_f32_16x16x32_bf16 v[122:125], v[140:143], v[172:175], v[122:125]
	v_mfma_f32_16x16x32_bf16 v[114:117], v[148:151], v[172:175], v[114:117]
	s_waitcnt lgkmcnt(5)
	v_mfma_f32_16x16x32_bf16 v[106:109], v[140:143], v[180:183], v[106:109]
	v_mfma_f32_16x16x32_bf16 v[98:101], v[148:151], v[180:183], v[98:101]
	s_waitcnt lgkmcnt(3)
	v_mfma_f32_16x16x32_bf16 v[90:93], v[140:143], v[188:191], v[90:93]
	v_mfma_f32_16x16x32_bf16 v[82:85], v[148:151], v[188:191], v[82:85]
	s_waitcnt lgkmcnt(1)
	v_mfma_f32_16x16x32_bf16 v[74:77], v[140:143], v[196:199], v[74:77]
	v_mfma_f32_16x16x32_bf16 v[66:69], v[148:151], v[196:199], v[66:69]
	v_mfma_f32_16x16x32_bf16 v[122:125], v[144:147], v[176:179], v[122:125]
	v_mfma_f32_16x16x32_bf16 v[114:117], v[152:155], v[176:179], v[114:117]
	v_mfma_f32_16x16x32_bf16 v[106:109], v[144:147], v[184:187], v[106:109]
	v_mfma_f32_16x16x32_bf16 v[98:101], v[152:155], v[184:187], v[98:101]
	v_mfma_f32_16x16x32_bf16 v[90:93], v[144:147], v[192:195], v[90:93]
	v_mfma_f32_16x16x32_bf16 v[82:85], v[152:155], v[192:195], v[82:85]
	s_waitcnt lgkmcnt(0)
	v_mfma_f32_16x16x32_bf16 v[74:77], v[144:147], v[200:203], v[74:77]
	v_mfma_f32_16x16x32_bf16 v[66:69], v[152:155], v[200:203], v[66:69]
	v_mfma_f32_16x16x32_bf16 v[126:129], v[156:159], v[172:175], v[126:129]
	v_mfma_f32_16x16x32_bf16 v[118:121], v[164:167], v[172:175], v[118:121]
	v_mfma_f32_16x16x32_bf16 v[110:113], v[156:159], v[180:183], v[110:113]
	v_mfma_f32_16x16x32_bf16 v[102:105], v[164:167], v[180:183], v[102:105]
	v_mfma_f32_16x16x32_bf16 v[94:97], v[156:159], v[188:191], v[94:97]
	v_mfma_f32_16x16x32_bf16 v[86:89], v[164:167], v[188:191], v[86:89]
	v_mfma_f32_16x16x32_bf16 v[78:81], v[156:159], v[196:199], v[78:81]
	v_mfma_f32_16x16x32_bf16 v[70:73], v[164:167], v[196:199], v[70:73]
	v_mfma_f32_16x16x32_bf16 v[126:129], v[160:163], v[176:179], v[126:129]
	v_mfma_f32_16x16x32_bf16 v[118:121], v[168:171], v[176:179], v[118:121]
	v_mfma_f32_16x16x32_bf16 v[110:113], v[160:163], v[184:187], v[110:113]
	v_mfma_f32_16x16x32_bf16 v[102:105], v[168:171], v[184:187], v[102:105]
	v_mfma_f32_16x16x32_bf16 v[94:97], v[160:163], v[192:195], v[94:97]
	v_mfma_f32_16x16x32_bf16 v[86:89], v[168:171], v[192:195], v[86:89]
	v_mfma_f32_16x16x32_bf16 v[78:81], v[160:163], v[200:203], v[78:81]
	v_mfma_f32_16x16x32_bf16 v[70:73], v[168:171], v[200:203], v[70:73]
	s_barrier
	s_add_u32 s52, s56, 0x20000
	ds_read_b128 v[172:175], v138 offset:16384
	ds_read_b128 v[176:179], v138 offset:17408
	ds_read_b128 v[180:183], v138 offset:18432
	ds_read_b128 v[184:187], v138 offset:19456
	ds_read_b128 v[188:191], v138 offset:20480
	ds_read_b128 v[192:195], v138 offset:21504
	ds_read_b128 v[196:199], v138 offset:22528
	ds_read_b128 v[200:203], v138 offset:23552
	s_mov_b32 m0, s62
	s_nop 0
	global_load_lds_dwordx4 v134, s[56:57]
	s_addc_u32 s53, s57, 0
	s_mov_b32 m0, s63
	s_nop 0
	global_load_lds_dwordx4 v134, s[52:53]
	s_add_u32 s52, s56, 0x40000
	s_addc_u32 s53, s57, 0
	s_mov_b32 m0, s64
	s_nop 0
	global_load_lds_dwordx4 v134, s[52:53]
	s_add_u32 s52, s56, 0x60000
	s_addc_u32 s53, s57, 0
	s_mov_b32 m0, s65
	s_nop 0
	global_load_lds_dwordx4 v134, s[52:53]
	s_add_u32 s52, s34, 0x20000
	s_mov_b32 m0, s51
	s_nop 0
	global_load_lds_dwordx4 v1, s[34:35]
	s_addc_u32 s53, s35, 0
	s_mov_b32 m0, s73
	s_nop 0
	global_load_lds_dwordx4 v1, s[52:53]
	s_waitcnt vmcnt(8)
	s_waitcnt lgkmcnt(0)
	s_barrier
	s_waitcnt lgkmcnt(7)
	v_mfma_f32_16x16x32_bf16 v[58:61], v[140:143], v[172:175], v[58:61]
	v_mfma_f32_16x16x32_bf16 v[50:53], v[148:151], v[172:175], v[50:53]
	s_waitcnt lgkmcnt(5)
	v_mfma_f32_16x16x32_bf16 v[42:45], v[140:143], v[180:183], v[42:45]
	v_mfma_f32_16x16x32_bf16 v[34:37], v[148:151], v[180:183], v[34:37]
	s_waitcnt lgkmcnt(3)
	v_mfma_f32_16x16x32_bf16 v[26:29], v[140:143], v[188:191], v[26:29]
	v_mfma_f32_16x16x32_bf16 v[18:21], v[148:151], v[188:191], v[18:21]
	s_waitcnt lgkmcnt(1)
	v_mfma_f32_16x16x32_bf16 v[10:13], v[140:143], v[196:199], v[10:13]
	v_mfma_f32_16x16x32_bf16 v[2:5], v[148:151], v[196:199], v[2:5]
	v_mfma_f32_16x16x32_bf16 v[58:61], v[144:147], v[176:179], v[58:61]
	v_mfma_f32_16x16x32_bf16 v[50:53], v[152:155], v[176:179], v[50:53]
	v_mfma_f32_16x16x32_bf16 v[42:45], v[144:147], v[184:187], v[42:45]
	v_mfma_f32_16x16x32_bf16 v[34:37], v[152:155], v[184:187], v[34:37]
	v_mfma_f32_16x16x32_bf16 v[26:29], v[144:147], v[192:195], v[26:29]
	v_mfma_f32_16x16x32_bf16 v[18:21], v[152:155], v[192:195], v[18:21]
	s_waitcnt lgkmcnt(0)
	v_mfma_f32_16x16x32_bf16 v[10:13], v[144:147], v[200:203], v[10:13]
	v_mfma_f32_16x16x32_bf16 v[2:5], v[152:155], v[200:203], v[2:5]
	v_mfma_f32_16x16x32_bf16 v[62:65], v[156:159], v[172:175], v[62:65]
	v_mfma_f32_16x16x32_bf16 v[54:57], v[164:167], v[172:175], v[54:57]
	v_mfma_f32_16x16x32_bf16 v[46:49], v[156:159], v[180:183], v[46:49]
	v_mfma_f32_16x16x32_bf16 v[38:41], v[164:167], v[180:183], v[38:41]
	v_mfma_f32_16x16x32_bf16 v[30:33], v[156:159], v[188:191], v[30:33]
	v_mfma_f32_16x16x32_bf16 v[22:25], v[164:167], v[188:191], v[22:25]
	v_mfma_f32_16x16x32_bf16 v[14:17], v[156:159], v[196:199], v[14:17]
	v_mfma_f32_16x16x32_bf16 v[6:9], v[164:167], v[196:199], v[6:9]
	v_mfma_f32_16x16x32_bf16 v[62:65], v[160:163], v[176:179], v[62:65]
	v_mfma_f32_16x16x32_bf16 v[54:57], v[168:171], v[176:179], v[54:57]
	v_mfma_f32_16x16x32_bf16 v[46:49], v[160:163], v[184:187], v[46:49]
	v_mfma_f32_16x16x32_bf16 v[38:41], v[168:171], v[184:187], v[38:41]
	v_mfma_f32_16x16x32_bf16 v[30:33], v[160:163], v[192:195], v[30:33]
	v_mfma_f32_16x16x32_bf16 v[22:25], v[168:171], v[192:195], v[22:25]
	v_mfma_f32_16x16x32_bf16 v[14:17], v[160:163], v[200:203], v[14:17]
	v_mfma_f32_16x16x32_bf16 v[6:9], v[168:171], v[200:203], v[6:9]
	s_barrier
	v_add_u32_e32 v139, 0x18000, v137
	ds_read_b128 v[140:143], v139
	ds_read_b128 v[144:147], v139 offset:1024
	ds_read_b128 v[148:151], v139 offset:2048
	ds_read_b128 v[152:155], v139 offset:3072
	v_add_u32_e32 v139, 0x1c000, v137
	ds_read_b128 v[156:159], v139
	ds_read_b128 v[160:163], v139 offset:1024
	ds_read_b128 v[164:167], v139 offset:2048
	ds_read_b128 v[168:171], v139 offset:3072
	ds_read_b128 v[172:175], v138 offset:32768
	ds_read_b128 v[176:179], v138 offset:33792
	ds_read_b128 v[180:183], v138 offset:34816
	ds_read_b128 v[184:187], v138 offset:35840
	ds_read_b128 v[188:191], v138 offset:36864
	ds_read_b128 v[192:195], v138 offset:37888
	ds_read_b128 v[196:199], v138 offset:38912
	ds_read_b128 v[200:203], v138 offset:39936
	s_add_u32 s52, s34, 0x40000
	s_addc_u32 s53, s35, 0
	s_mov_b32 m0, s74
	s_nop 0
	global_load_lds_dwordx4 v1, s[52:53]
	s_add_u32 s52, s34, 0x60000
	s_addc_u32 s53, s35, 0
	s_mov_b32 m0, s75
	s_nop 0
	global_load_lds_dwordx4 v1, s[52:53]
	s_waitcnt vmcnt(8)
	s_waitcnt lgkmcnt(0)
	s_barrier
	s_waitcnt lgkmcnt(7)
	v_mfma_f32_16x16x32_bf16 v[122:125], v[140:143], v[172:175], v[122:125]
	v_mfma_f32_16x16x32_bf16 v[114:117], v[148:151], v[172:175], v[114:117]
	s_waitcnt lgkmcnt(5)
	v_mfma_f32_16x16x32_bf16 v[106:109], v[140:143], v[180:183], v[106:109]
	v_mfma_f32_16x16x32_bf16 v[98:101], v[148:151], v[180:183], v[98:101]
	s_waitcnt lgkmcnt(3)
	v_mfma_f32_16x16x32_bf16 v[90:93], v[140:143], v[188:191], v[90:93]
	v_mfma_f32_16x16x32_bf16 v[82:85], v[148:151], v[188:191], v[82:85]
	s_waitcnt lgkmcnt(1)
	v_mfma_f32_16x16x32_bf16 v[74:77], v[140:143], v[196:199], v[74:77]
	v_mfma_f32_16x16x32_bf16 v[66:69], v[148:151], v[196:199], v[66:69]
	v_mfma_f32_16x16x32_bf16 v[122:125], v[144:147], v[176:179], v[122:125]
	v_mfma_f32_16x16x32_bf16 v[114:117], v[152:155], v[176:179], v[114:117]
	v_mfma_f32_16x16x32_bf16 v[106:109], v[144:147], v[184:187], v[106:109]
	v_mfma_f32_16x16x32_bf16 v[98:101], v[152:155], v[184:187], v[98:101]
	v_mfma_f32_16x16x32_bf16 v[90:93], v[144:147], v[192:195], v[90:93]
	v_mfma_f32_16x16x32_bf16 v[82:85], v[152:155], v[192:195], v[82:85]
	s_waitcnt lgkmcnt(0)
	v_mfma_f32_16x16x32_bf16 v[74:77], v[144:147], v[200:203], v[74:77]
	v_mfma_f32_16x16x32_bf16 v[66:69], v[152:155], v[200:203], v[66:69]
	v_mfma_f32_16x16x32_bf16 v[126:129], v[156:159], v[172:175], v[126:129]
	v_mfma_f32_16x16x32_bf16 v[118:121], v[164:167], v[172:175], v[118:121]
	v_mfma_f32_16x16x32_bf16 v[110:113], v[156:159], v[180:183], v[110:113]
	v_mfma_f32_16x16x32_bf16 v[102:105], v[164:167], v[180:183], v[102:105]
	v_mfma_f32_16x16x32_bf16 v[94:97], v[156:159], v[188:191], v[94:97]
	v_mfma_f32_16x16x32_bf16 v[86:89], v[164:167], v[188:191], v[86:89]
	v_mfma_f32_16x16x32_bf16 v[78:81], v[156:159], v[196:199], v[78:81]
	v_mfma_f32_16x16x32_bf16 v[70:73], v[164:167], v[196:199], v[70:73]
	v_mfma_f32_16x16x32_bf16 v[126:129], v[160:163], v[176:179], v[126:129]
	v_mfma_f32_16x16x32_bf16 v[118:121], v[168:171], v[176:179], v[118:121]
	v_mfma_f32_16x16x32_bf16 v[110:113], v[160:163], v[184:187], v[110:113]
	v_mfma_f32_16x16x32_bf16 v[102:105], v[168:171], v[184:187], v[102:105]
	v_mfma_f32_16x16x32_bf16 v[94:97], v[160:163], v[192:195], v[94:97]
	v_mfma_f32_16x16x32_bf16 v[86:89], v[168:171], v[192:195], v[86:89]
	v_mfma_f32_16x16x32_bf16 v[78:81], v[160:163], v[200:203], v[78:81]
	v_mfma_f32_16x16x32_bf16 v[70:73], v[168:171], v[200:203], v[70:73]
	s_barrier
	s_add_u32 s52, s56, 0x80
	s_addc_u32 s53, s57, 0
	ds_read_b128 v[172:175], v138 offset:49152
	ds_read_b128 v[176:179], v138 offset:50176
	ds_read_b128 v[180:183], v138 offset:51200
	ds_read_b128 v[184:187], v138 offset:52224
	ds_read_b128 v[188:191], v138 offset:53248
	ds_read_b128 v[192:195], v138 offset:54272
	ds_read_b128 v[196:199], v138 offset:55296
	ds_read_b128 v[200:203], v138 offset:56320
	s_mov_b32 m0, s76
	s_nop 0
	global_load_lds_dwordx4 v134, s[52:53]
	s_add_u32 s52, s56, 0x20080
	s_addc_u32 s53, s57, 0
	s_mov_b32 m0, s77
	s_nop 0
	global_load_lds_dwordx4 v134, s[52:53]
	s_add_u32 s52, s56, 0x40080
	s_addc_u32 s53, s57, 0
	s_mov_b32 m0, s80
	s_nop 0
	global_load_lds_dwordx4 v134, s[52:53]
	s_add_u32 s52, s56, 0x60080
	s_addc_u32 s53, s57, 0
	s_mov_b32 m0, s81
	s_nop 0
	global_load_lds_dwordx4 v134, s[52:53]
	s_add_u32 s34, s34, 0x20080
	s_mov_b32 m0, s78
	s_nop 0
	global_load_lds_dwordx4 v1, s[54:55]
	s_addc_u32 s35, s35, 0
	s_mov_b32 m0, s79
	s_nop 0
	global_load_lds_dwordx4 v1, s[34:35]
	s_waitcnt vmcnt(8)
	s_waitcnt lgkmcnt(0)
	s_barrier
	s_waitcnt lgkmcnt(7)
	v_mfma_f32_16x16x32_bf16 v[58:61], v[140:143], v[172:175], v[58:61]
	v_mfma_f32_16x16x32_bf16 v[50:53], v[148:151], v[172:175], v[50:53]
	s_waitcnt lgkmcnt(5)
	v_mfma_f32_16x16x32_bf16 v[42:45], v[140:143], v[180:183], v[42:45]
	v_mfma_f32_16x16x32_bf16 v[34:37], v[148:151], v[180:183], v[34:37]
	s_waitcnt lgkmcnt(3)
	v_mfma_f32_16x16x32_bf16 v[26:29], v[140:143], v[188:191], v[26:29]
	v_mfma_f32_16x16x32_bf16 v[18:21], v[148:151], v[188:191], v[18:21]
	s_waitcnt lgkmcnt(1)
	v_mfma_f32_16x16x32_bf16 v[10:13], v[140:143], v[196:199], v[10:13]
	v_mfma_f32_16x16x32_bf16 v[2:5], v[148:151], v[196:199], v[2:5]
	v_mfma_f32_16x16x32_bf16 v[58:61], v[144:147], v[176:179], v[58:61]
	v_mfma_f32_16x16x32_bf16 v[50:53], v[152:155], v[176:179], v[50:53]
	v_mfma_f32_16x16x32_bf16 v[42:45], v[144:147], v[184:187], v[42:45]
	v_mfma_f32_16x16x32_bf16 v[34:37], v[152:155], v[184:187], v[34:37]
	v_mfma_f32_16x16x32_bf16 v[26:29], v[144:147], v[192:195], v[26:29]
	v_mfma_f32_16x16x32_bf16 v[18:21], v[152:155], v[192:195], v[18:21]
	s_waitcnt lgkmcnt(0)
	v_mfma_f32_16x16x32_bf16 v[10:13], v[144:147], v[200:203], v[10:13]
	v_mfma_f32_16x16x32_bf16 v[2:5], v[152:155], v[200:203], v[2:5]
	v_mfma_f32_16x16x32_bf16 v[62:65], v[156:159], v[172:175], v[62:65]
	v_mfma_f32_16x16x32_bf16 v[54:57], v[164:167], v[172:175], v[54:57]
	v_mfma_f32_16x16x32_bf16 v[46:49], v[156:159], v[180:183], v[46:49]
	v_mfma_f32_16x16x32_bf16 v[38:41], v[164:167], v[180:183], v[38:41]
	v_mfma_f32_16x16x32_bf16 v[30:33], v[156:159], v[188:191], v[30:33]
	v_mfma_f32_16x16x32_bf16 v[22:25], v[164:167], v[188:191], v[22:25]
	v_mfma_f32_16x16x32_bf16 v[14:17], v[156:159], v[196:199], v[14:17]
	v_mfma_f32_16x16x32_bf16 v[6:9], v[164:167], v[196:199], v[6:9]
	v_mfma_f32_16x16x32_bf16 v[62:65], v[160:163], v[176:179], v[62:65]
	v_mfma_f32_16x16x32_bf16 v[54:57], v[168:171], v[176:179], v[54:57]
	v_mfma_f32_16x16x32_bf16 v[46:49], v[160:163], v[184:187], v[46:49]
	v_mfma_f32_16x16x32_bf16 v[38:41], v[168:171], v[184:187], v[38:41]
	v_mfma_f32_16x16x32_bf16 v[30:33], v[160:163], v[192:195], v[30:33]
	v_mfma_f32_16x16x32_bf16 v[22:25], v[168:171], v[192:195], v[22:25]
	v_mfma_f32_16x16x32_bf16 v[14:17], v[160:163], v[200:203], v[14:17]
	v_mfma_f32_16x16x32_bf16 v[6:9], v[168:171], v[200:203], v[6:9]
	s_barrier
	s_add_i32 s89, s89, 2
	s_add_u32 s87, s87, 0x100
	s_addc_u32 s88, s88, 0
	s_cmp_gt_u32 s89, 13
	s_mov_b64 s[52:53], s[0:1]
	s_cbranch_scc0 .LBB0_156
	s_and_b64 vcc, exec, s[8:9]
	s_cbranch_vccz .LBB0_159
	s_barrier

.LBB0_236:
	ds_read_b128 v[138:141], v132
	ds_read_b128 v[142:145], v132 offset:1024
	ds_read_b128 v[146:149], v132 offset:2048
	ds_read_b128 v[150:153], v132 offset:3072
	ds_read_b128 v[154:157], v133
	ds_read_b128 v[158:161], v133 offset:1024
	ds_read_b128 v[166:169], v133 offset:2048
	ds_read_b128 v[170:173], v133 offset:3072
	s_add_u32 s0, s52, 0xea350080
	s_addc_u32 s1, s53, -1
	s_cmp_lg_u32 s92, 40
	s_cselect_b32 s3, s0, 0
	s_cselect_b32 s2, s1, 0
	s_add_u32 s0, s10, s3
	s_addc_u32 s1, s11, s2
	s_add_u32 s34, s0, 0x80
	s_addc_u32 s35, s1, 0
	s_add_u32 s54, s6, s3
	s_addc_u32 s55, s7, s2
	ds_read_b128 v[174:177], v134
	ds_read_b128 v[184:187], v134 offset:1024
	ds_read_b128 v[188:191], v134 offset:2048
	ds_read_b128 v[192:195], v134 offset:3072
	ds_read_b128 v[196:199], v134 offset:4096
	ds_read_b128 v[200:203], v134 offset:5120
	ds_read_b128 v[204:207], v134 offset:6144
	ds_read_b128 v[208:211], v134 offset:7168
	s_add_u32 s94, s90, s52
	s_addc_u32 s95, s91, s53
	s_mov_b32 m0, s89
	s_nop 0
	global_load_lds_dwordx4 v130, s[94:95]
	s_add_u32 s94, s94, 0x58000
	s_addc_u32 s95, s95, 0
	s_add_i32 s2, s65, 0xe000
	s_mov_b32 m0, s2
	s_nop 0
	global_load_lds_dwordx4 v130, s[94:95]
	s_waitcnt vmcnt(8)
	s_waitcnt lgkmcnt(0)
	s_barrier
	s_waitcnt lgkmcnt(7)
	v_mfma_f32_16x16x32_bf16 v[2:5], v[138:141], v[174:177], v[2:5]
	v_mfma_f32_16x16x32_bf16 v[6:9], v[146:149], v[174:177], v[6:9]
	s_waitcnt lgkmcnt(5)
	v_mfma_f32_16x16x32_bf16 v[30:33], v[138:141], v[188:191], v[30:33]
	v_mfma_f32_16x16x32_bf16 v[34:37], v[146:149], v[188:191], v[34:37]
	s_waitcnt lgkmcnt(3)
	v_mfma_f32_16x16x32_bf16 v[54:57], v[138:141], v[196:199], v[54:57]
	v_mfma_f32_16x16x32_bf16 v[50:53], v[146:149], v[196:199], v[50:53]
	s_waitcnt lgkmcnt(1)
	v_mfma_f32_16x16x32_bf16 v[70:73], v[138:141], v[204:207], v[70:73]
	v_mfma_f32_16x16x32_bf16 v[62:65], v[146:149], v[204:207], v[62:65]
	v_mfma_f32_16x16x32_bf16 v[2:5], v[142:145], v[184:187], v[2:5]
	v_mfma_f32_16x16x32_bf16 v[6:9], v[150:153], v[184:187], v[6:9]
	v_mfma_f32_16x16x32_bf16 v[30:33], v[142:145], v[192:195], v[30:33]
	v_mfma_f32_16x16x32_bf16 v[34:37], v[150:153], v[192:195], v[34:37]
	v_mfma_f32_16x16x32_bf16 v[54:57], v[142:145], v[200:203], v[54:57]
	v_mfma_f32_16x16x32_bf16 v[50:53], v[150:153], v[200:203], v[50:53]
	s_waitcnt lgkmcnt(0)
	v_mfma_f32_16x16x32_bf16 v[70:73], v[142:145], v[208:211], v[70:73]
	v_mfma_f32_16x16x32_bf16 v[62:65], v[150:153], v[208:211], v[62:65]
	v_mfma_f32_16x16x32_bf16 v[10:13], v[154:157], v[174:177], v[10:13]
	v_mfma_f32_16x16x32_bf16 v[14:17], v[166:169], v[174:177], v[14:17]
	v_mfma_f32_16x16x32_bf16 v[22:25], v[154:157], v[188:191], v[22:25]
	v_mfma_f32_16x16x32_bf16 v[18:21], v[166:169], v[188:191], v[18:21]
	v_mfma_f32_16x16x32_bf16 v[38:41], v[154:157], v[196:199], v[38:41]
	v_mfma_f32_16x16x32_bf16 v[26:29], v[166:169], v[196:199], v[26:29]
	v_mfma_f32_16x16x32_bf16 v[46:49], v[154:157], v[204:207], v[46:49]
	v_mfma_f32_16x16x32_bf16 v[42:45], v[166:169], v[204:207], v[42:45]
	v_mfma_f32_16x16x32_bf16 v[10:13], v[158:161], v[184:187], v[10:13]
	v_mfma_f32_16x16x32_bf16 v[14:17], v[170:173], v[184:187], v[14:17]
	v_mfma_f32_16x16x32_bf16 v[22:25], v[158:161], v[192:195], v[22:25]
	v_mfma_f32_16x16x32_bf16 v[18:21], v[170:173], v[192:195], v[18:21]
	v_mfma_f32_16x16x32_bf16 v[38:41], v[158:161], v[200:203], v[38:41]
	v_mfma_f32_16x16x32_bf16 v[26:29], v[170:173], v[200:203], v[26:29]
	v_mfma_f32_16x16x32_bf16 v[46:49], v[158:161], v[208:211], v[46:49]
	v_mfma_f32_16x16x32_bf16 v[42:45], v[170:173], v[208:211], v[42:45]
	s_barrier
	s_add_u32 s94, s54, 0x58000
	ds_read_b128 v[174:177], v134 offset:16384
	ds_read_b128 v[184:187], v134 offset:17408
	ds_read_b128 v[188:191], v134 offset:18432
	ds_read_b128 v[192:195], v134 offset:19456
	ds_read_b128 v[196:199], v134 offset:20480
	ds_read_b128 v[200:203], v134 offset:21504
	ds_read_b128 v[204:207], v134 offset:22528
	ds_read_b128 v[208:211], v134 offset:23552
	s_mov_b32 m0, s73
	s_nop 0
	global_load_lds_dwordx4 v131, s[54:55]
	s_addc_u32 s95, s55, 0
	s_mov_b32 m0, s74
	s_nop 0
	global_load_lds_dwordx4 v131, s[94:95]
	s_add_u32 s94, s54, 0xb0000
	s_addc_u32 s95, s55, 0
	s_mov_b32 m0, s75
	s_nop 0
	global_load_lds_dwordx4 v131, s[94:95]
	s_add_u32 s94, s54, 0x108000
	s_addc_u32 s95, s55, 0
	s_mov_b32 m0, s76
	s_nop 0
	global_load_lds_dwordx4 v131, s[94:95]
	s_add_u32 s94, s0, 0x58000
	s_mov_b32 m0, s65
	s_nop 0
	global_load_lds_dwordx4 v130, s[0:1]
	s_addc_u32 s95, s1, 0
	s_mov_b32 m0, s77
	s_nop 0
	global_load_lds_dwordx4 v130, s[94:95]
	s_waitcnt vmcnt(8)
	s_waitcnt lgkmcnt(0)
	s_barrier
	s_waitcnt lgkmcnt(7)
	v_mfma_f32_16x16x32_bf16 v[82:85], v[138:141], v[174:177], v[82:85]
	v_mfma_f32_16x16x32_bf16 v[74:77], v[146:149], v[174:177], v[74:77]
	s_waitcnt lgkmcnt(5)
	v_mfma_f32_16x16x32_bf16 v[98:101], v[138:141], v[188:191], v[98:101]
	v_mfma_f32_16x16x32_bf16 v[90:93], v[146:149], v[188:191], v[90:93]
	s_waitcnt lgkmcnt(3)
	v_mfma_f32_16x16x32_bf16 v[114:117], v[138:141], v[196:199], v[114:117]
	v_mfma_f32_16x16x32_bf16 v[110:113], v[146:149], v[196:199], v[110:113]
	s_waitcnt lgkmcnt(1)
	v_mfma_f32_16x16x32_bf16 v[126:129], v[138:141], v[204:207], v[126:129]
	v_mfma_f32_16x16x32_bf16 v[122:125], v[146:149], v[204:207], v[122:125]
	v_mfma_f32_16x16x32_bf16 v[82:85], v[142:145], v[184:187], v[82:85]
	v_mfma_f32_16x16x32_bf16 v[74:77], v[150:153], v[184:187], v[74:77]
	v_mfma_f32_16x16x32_bf16 v[98:101], v[142:145], v[192:195], v[98:101]
	v_mfma_f32_16x16x32_bf16 v[90:93], v[150:153], v[192:195], v[90:93]
	v_mfma_f32_16x16x32_bf16 v[114:117], v[142:145], v[200:203], v[114:117]
	v_mfma_f32_16x16x32_bf16 v[110:113], v[150:153], v[200:203], v[110:113]
	s_waitcnt lgkmcnt(0)
	v_mfma_f32_16x16x32_bf16 v[126:129], v[142:145], v[208:211], v[126:129]
	v_mfma_f32_16x16x32_bf16 v[122:125], v[150:153], v[208:211], v[122:125]
	v_mfma_f32_16x16x32_bf16 v[66:69], v[154:157], v[174:177], v[66:69]
	v_mfma_f32_16x16x32_bf16 v[58:61], v[166:169], v[174:177], v[58:61]
	v_mfma_f32_16x16x32_bf16 v[86:89], v[154:157], v[188:191], v[86:89]
	v_mfma_f32_16x16x32_bf16 v[78:81], v[166:169], v[188:191], v[78:81]
	v_mfma_f32_16x16x32_bf16 v[102:105], v[154:157], v[196:199], v[102:105]
	v_mfma_f32_16x16x32_bf16 v[94:97], v[166:169], v[196:199], v[94:97]
	v_mfma_f32_16x16x32_bf16 v[118:121], v[154:157], v[204:207], v[118:121]
	v_mfma_f32_16x16x32_bf16 v[106:109], v[166:169], v[204:207], v[106:109]
	v_mfma_f32_16x16x32_bf16 v[66:69], v[158:161], v[184:187], v[66:69]
	v_mfma_f32_16x16x32_bf16 v[58:61], v[170:173], v[184:187], v[58:61]
	v_mfma_f32_16x16x32_bf16 v[86:89], v[158:161], v[192:195], v[86:89]
	v_mfma_f32_16x16x32_bf16 v[78:81], v[170:173], v[192:195], v[78:81]
	v_mfma_f32_16x16x32_bf16 v[102:105], v[158:161], v[200:203], v[102:105]
	v_mfma_f32_16x16x32_bf16 v[94:97], v[170:173], v[200:203], v[94:97]
	v_mfma_f32_16x16x32_bf16 v[118:121], v[158:161], v[208:211], v[118:121]
	v_mfma_f32_16x16x32_bf16 v[106:109], v[170:173], v[208:211], v[106:109]
	s_barrier
	ds_read_b128 v[138:141], v135
	ds_read_b128 v[142:145], v135 offset:1024
	ds_read_b128 v[146:149], v135 offset:2048
	ds_read_b128 v[150:153], v135 offset:3072
	ds_read_b128 v[154:157], v136
	ds_read_b128 v[158:161], v136 offset:1024
	ds_read_b128 v[166:169], v136 offset:2048
	ds_read_b128 v[170:173], v136 offset:3072
	ds_read_b128 v[174:177], v134 offset:32768
	ds_read_b128 v[184:187], v134 offset:33792
	ds_read_b128 v[188:191], v134 offset:34816
	ds_read_b128 v[192:195], v134 offset:35840
	ds_read_b128 v[196:199], v134 offset:36864
	ds_read_b128 v[200:203], v134 offset:37888
	ds_read_b128 v[204:207], v134 offset:38912
	ds_read_b128 v[208:211], v134 offset:39936
	s_add_u32 s94, s0, 0xb0000
	s_addc_u32 s95, s1, 0
	s_mov_b32 m0, s78
	s_nop 0
	global_load_lds_dwordx4 v130, s[94:95]
	s_add_u32 s94, s0, 0x108000
	s_addc_u32 s95, s1, 0
	s_mov_b32 m0, s80
	s_nop 0
	global_load_lds_dwordx4 v130, s[94:95]
	s_waitcnt vmcnt(8)
	s_waitcnt lgkmcnt(0)
	s_barrier
	s_waitcnt lgkmcnt(7)
	v_mfma_f32_16x16x32_bf16 v[2:5], v[138:141], v[174:177], v[2:5]
	v_mfma_f32_16x16x32_bf16 v[6:9], v[146:149], v[174:177], v[6:9]
	s_waitcnt lgkmcnt(5)
	v_mfma_f32_16x16x32_bf16 v[30:33], v[138:141], v[188:191], v[30:33]
	v_mfma_f32_16x16x32_bf16 v[34:37], v[146:149], v[188:191], v[34:37]
	s_waitcnt lgkmcnt(3)
	v_mfma_f32_16x16x32_bf16 v[54:57], v[138:141], v[196:199], v[54:57]
	v_mfma_f32_16x16x32_bf16 v[50:53], v[146:149], v[196:199], v[50:53]
	s_waitcnt lgkmcnt(1)
	v_mfma_f32_16x16x32_bf16 v[70:73], v[138:141], v[204:207], v[70:73]
	v_mfma_f32_16x16x32_bf16 v[62:65], v[146:149], v[204:207], v[62:65]
	v_mfma_f32_16x16x32_bf16 v[2:5], v[142:145], v[184:187], v[2:5]
	v_mfma_f32_16x16x32_bf16 v[6:9], v[150:153], v[184:187], v[6:9]
	v_mfma_f32_16x16x32_bf16 v[30:33], v[142:145], v[192:195], v[30:33]
	v_mfma_f32_16x16x32_bf16 v[34:37], v[150:153], v[192:195], v[34:37]
	v_mfma_f32_16x16x32_bf16 v[54:57], v[142:145], v[200:203], v[54:57]
	v_mfma_f32_16x16x32_bf16 v[50:53], v[150:153], v[200:203], v[50:53]
	s_waitcnt lgkmcnt(0)
	v_mfma_f32_16x16x32_bf16 v[70:73], v[142:145], v[208:211], v[70:73]
	v_mfma_f32_16x16x32_bf16 v[62:65], v[150:153], v[208:211], v[62:65]
	v_mfma_f32_16x16x32_bf16 v[10:13], v[154:157], v[174:177], v[10:13]
	v_mfma_f32_16x16x32_bf16 v[14:17], v[166:169], v[174:177], v[14:17]
	v_mfma_f32_16x16x32_bf16 v[22:25], v[154:157], v[188:191], v[22:25]
	v_mfma_f32_16x16x32_bf16 v[18:21], v[166:169], v[188:191], v[18:21]
	v_mfma_f32_16x16x32_bf16 v[38:41], v[154:157], v[196:199], v[38:41]
	v_mfma_f32_16x16x32_bf16 v[26:29], v[166:169], v[196:199], v[26:29]
	v_mfma_f32_16x16x32_bf16 v[46:49], v[154:157], v[204:207], v[46:49]
	v_mfma_f32_16x16x32_bf16 v[42:45], v[166:169], v[204:207], v[42:45]
	v_mfma_f32_16x16x32_bf16 v[10:13], v[158:161], v[184:187], v[10:13]
	v_mfma_f32_16x16x32_bf16 v[14:17], v[170:173], v[184:187], v[14:17]
	v_mfma_f32_16x16x32_bf16 v[22:25], v[158:161], v[192:195], v[22:25]
	v_mfma_f32_16x16x32_bf16 v[18:21], v[170:173], v[192:195], v[18:21]
	v_mfma_f32_16x16x32_bf16 v[38:41], v[158:161], v[200:203], v[38:41]
	v_mfma_f32_16x16x32_bf16 v[26:29], v[170:173], v[200:203], v[26:29]
	v_mfma_f32_16x16x32_bf16 v[46:49], v[158:161], v[208:211], v[46:49]
	v_mfma_f32_16x16x32_bf16 v[42:45], v[170:173], v[208:211], v[42:45]
	s_barrier
	s_add_u32 s94, s54, 0x80
	s_addc_u32 s95, s55, 0
	ds_read_b128 v[174:177], v134 offset:49152
	ds_read_b128 v[184:187], v134 offset:50176
	ds_read_b128 v[188:191], v134 offset:51200
	ds_read_b128 v[192:195], v134 offset:52224
	ds_read_b128 v[196:199], v134 offset:53248
	ds_read_b128 v[200:203], v134 offset:54272
	ds_read_b128 v[204:207], v134 offset:55296
	ds_read_b128 v[208:211], v134 offset:56320
	s_mov_b32 m0, s81
	s_nop 0
	global_load_lds_dwordx4 v131, s[94:95]
	s_add_u32 s94, s54, 0x58080
	s_addc_u32 s95, s55, 0
	s_mov_b32 m0, s84
	s_nop 0
	global_load_lds_dwordx4 v131, s[94:95]
	s_add_u32 s94, s54, 0xb0080
	s_addc_u32 s95, s55, 0
	s_mov_b32 m0, s87
	s_nop 0
	global_load_lds_dwordx4 v131, s[94:95]
	s_add_u32 s54, s54, 0x108080
	s_addc_u32 s55, s55, 0
	s_mov_b32 m0, s88
	s_nop 0
	global_load_lds_dwordx4 v131, s[54:55]
	s_add_u32 s0, s0, 0x58080
	s_mov_b32 m0, s85
	s_nop 0
	global_load_lds_dwordx4 v130, s[34:35]
	s_addc_u32 s1, s1, 0
	s_mov_b32 m0, s86
	s_nop 0
	global_load_lds_dwordx4 v130, s[0:1]
	s_waitcnt vmcnt(8)
	s_waitcnt lgkmcnt(0)
	s_barrier
	s_waitcnt lgkmcnt(7)
	v_mfma_f32_16x16x32_bf16 v[82:85], v[138:141], v[174:177], v[82:85]
	v_mfma_f32_16x16x32_bf16 v[74:77], v[146:149], v[174:177], v[74:77]
	s_waitcnt lgkmcnt(5)
	v_mfma_f32_16x16x32_bf16 v[98:101], v[138:141], v[188:191], v[98:101]
	v_mfma_f32_16x16x32_bf16 v[90:93], v[146:149], v[188:191], v[90:93]
	s_waitcnt lgkmcnt(3)
	v_mfma_f32_16x16x32_bf16 v[114:117], v[138:141], v[196:199], v[114:117]
	v_mfma_f32_16x16x32_bf16 v[110:113], v[146:149], v[196:199], v[110:113]
	s_waitcnt lgkmcnt(1)
	v_mfma_f32_16x16x32_bf16 v[126:129], v[138:141], v[204:207], v[126:129]
	v_mfma_f32_16x16x32_bf16 v[122:125], v[146:149], v[204:207], v[122:125]
	v_mfma_f32_16x16x32_bf16 v[82:85], v[142:145], v[184:187], v[82:85]
	v_mfma_f32_16x16x32_bf16 v[74:77], v[150:153], v[184:187], v[74:77]
	v_mfma_f32_16x16x32_bf16 v[98:101], v[142:145], v[192:195], v[98:101]
	v_mfma_f32_16x16x32_bf16 v[90:93], v[150:153], v[192:195], v[90:93]
	v_mfma_f32_16x16x32_bf16 v[114:117], v[142:145], v[200:203], v[114:117]
	v_mfma_f32_16x16x32_bf16 v[110:113], v[150:153], v[200:203], v[110:113]
	s_waitcnt lgkmcnt(0)
	v_mfma_f32_16x16x32_bf16 v[126:129], v[142:145], v[208:211], v[126:129]
	v_mfma_f32_16x16x32_bf16 v[122:125], v[150:153], v[208:211], v[122:125]
	v_mfma_f32_16x16x32_bf16 v[66:69], v[154:157], v[174:177], v[66:69]
	v_mfma_f32_16x16x32_bf16 v[58:61], v[166:169], v[174:177], v[58:61]
	v_mfma_f32_16x16x32_bf16 v[86:89], v[154:157], v[188:191], v[86:89]
	v_mfma_f32_16x16x32_bf16 v[78:81], v[166:169], v[188:191], v[78:81]
	v_mfma_f32_16x16x32_bf16 v[102:105], v[154:157], v[196:199], v[102:105]
	v_mfma_f32_16x16x32_bf16 v[94:97], v[166:169], v[196:199], v[94:97]
	v_mfma_f32_16x16x32_bf16 v[118:121], v[154:157], v[204:207], v[118:121]
	v_mfma_f32_16x16x32_bf16 v[106:109], v[166:169], v[204:207], v[106:109]
	v_mfma_f32_16x16x32_bf16 v[66:69], v[158:161], v[184:187], v[66:69]
	v_mfma_f32_16x16x32_bf16 v[58:61], v[170:173], v[184:187], v[58:61]
	v_mfma_f32_16x16x32_bf16 v[86:89], v[158:161], v[192:195], v[86:89]
	v_mfma_f32_16x16x32_bf16 v[78:81], v[170:173], v[192:195], v[78:81]
	v_mfma_f32_16x16x32_bf16 v[102:105], v[158:161], v[200:203], v[102:105]
	v_mfma_f32_16x16x32_bf16 v[94:97], v[170:173], v[200:203], v[94:97]
	v_mfma_f32_16x16x32_bf16 v[118:121], v[158:161], v[208:211], v[118:121]
	v_mfma_f32_16x16x32_bf16 v[106:109], v[170:173], v[208:211], v[106:109]
	s_barrier
	s_add_i32 s92, s92, 2
	s_add_u32 s52, s52, 0x100
	s_addc_u32 s53, s53, 0
	s_cmp_lt_u32 s92, 42
	s_cbranch_scc1 .LBB0_236
	s_waitcnt vmcnt(0)
	s_cmpk_gt_u32 s63, 0xff
	s_cbranch_scc1 .LBB0_239
	s_barrier

.LBB0_419:
	v_add_u32_e32 v134, 0x10000, v145
	ds_read_b128 v[136:139], v134
	ds_read_b128 v[148:151], v134 offset:1024
	ds_read_b128 v[152:155], v134 offset:2048
	ds_read_b128 v[156:159], v134 offset:3072
	v_add_u32_e32 v134, 0x14000, v145
	ds_read_b128 v[160:163], v134
	ds_read_b128 v[164:167], v134 offset:1024
	ds_read_b128 v[168:171], v134 offset:2048
	ds_read_b128 v[172:175], v134 offset:3072
	s_add_u32 s0, s50, 0x100
	s_addc_u32 s1, s51, 0
	s_cmp_eq_u32 s81, 12
	s_cselect_b32 s34, s15, s0
	s_cselect_b32 s35, s14, s1
	s_cselect_b32 s54, s37, s79
	s_cselect_b32 s55, s27, s80
	s_add_u32 s52, s34, 0x80
	s_addc_u32 s53, s35, 0
	ds_read_b128 v[176:179], v146
	ds_read_b128 v[180:183], v146 offset:1024
	ds_read_b128 v[184:187], v146 offset:2048
	ds_read_b128 v[188:191], v146 offset:3072
	ds_read_b128 v[192:195], v146 offset:4096
	ds_read_b128 v[196:199], v146 offset:5120
	ds_read_b128 v[200:203], v146 offset:6144
	ds_read_b128 v[204:207], v146 offset:7168
	s_add_u32 s84, s50, 0x40080
	s_addc_u32 s85, s51, 0
	s_mov_b32 m0, s76
	s_nop 0
	global_load_lds_dwordx4 v1, s[84:85]
	s_add_u32 s50, s50, 0x60080
	s_addc_u32 s51, s51, 0
	s_add_i32 s2, s45, 0xe000
	s_mov_b32 m0, s2
	s_nop 0
	global_load_lds_dwordx4 v1, s[50:51]
	s_waitcnt vmcnt(8)
	s_waitcnt lgkmcnt(0)
	s_barrier
	s_waitcnt lgkmcnt(7)
	v_mfma_f32_16x16x32_bf16 v[122:125], v[136:139], v[176:179], v[122:125]
	v_mfma_f32_16x16x32_bf16 v[114:117], v[152:155], v[176:179], v[114:117]
	s_waitcnt lgkmcnt(5)
	v_mfma_f32_16x16x32_bf16 v[106:109], v[136:139], v[184:187], v[106:109]
	v_mfma_f32_16x16x32_bf16 v[98:101], v[152:155], v[184:187], v[98:101]
	s_waitcnt lgkmcnt(3)
	v_mfma_f32_16x16x32_bf16 v[90:93], v[136:139], v[192:195], v[90:93]
	v_mfma_f32_16x16x32_bf16 v[82:85], v[152:155], v[192:195], v[82:85]
	s_waitcnt lgkmcnt(1)
	v_mfma_f32_16x16x32_bf16 v[74:77], v[136:139], v[200:203], v[74:77]
	v_mfma_f32_16x16x32_bf16 v[66:69], v[152:155], v[200:203], v[66:69]
	v_mfma_f32_16x16x32_bf16 v[122:125], v[148:151], v[180:183], v[122:125]
	v_mfma_f32_16x16x32_bf16 v[114:117], v[156:159], v[180:183], v[114:117]
	v_mfma_f32_16x16x32_bf16 v[106:109], v[148:151], v[188:191], v[106:109]
	v_mfma_f32_16x16x32_bf16 v[98:101], v[156:159], v[188:191], v[98:101]
	v_mfma_f32_16x16x32_bf16 v[90:93], v[148:151], v[196:199], v[90:93]
	v_mfma_f32_16x16x32_bf16 v[82:85], v[156:159], v[196:199], v[82:85]
	s_waitcnt lgkmcnt(0)
	v_mfma_f32_16x16x32_bf16 v[74:77], v[148:151], v[204:207], v[74:77]
	v_mfma_f32_16x16x32_bf16 v[66:69], v[156:159], v[204:207], v[66:69]
	v_mfma_f32_16x16x32_bf16 v[126:129], v[160:163], v[176:179], v[126:129]
	v_mfma_f32_16x16x32_bf16 v[118:121], v[168:171], v[176:179], v[118:121]
	v_mfma_f32_16x16x32_bf16 v[110:113], v[160:163], v[184:187], v[110:113]
	v_mfma_f32_16x16x32_bf16 v[102:105], v[168:171], v[184:187], v[102:105]
	v_mfma_f32_16x16x32_bf16 v[94:97], v[160:163], v[192:195], v[94:97]
	v_mfma_f32_16x16x32_bf16 v[86:89], v[168:171], v[192:195], v[86:89]
	v_mfma_f32_16x16x32_bf16 v[78:81], v[160:163], v[200:203], v[78:81]
	v_mfma_f32_16x16x32_bf16 v[70:73], v[168:171], v[200:203], v[70:73]
	v_mfma_f32_16x16x32_bf16 v[126:129], v[164:167], v[180:183], v[126:129]
	v_mfma_f32_16x16x32_bf16 v[118:121], v[172:175], v[180:183], v[118:121]
	v_mfma_f32_16x16x32_bf16 v[110:113], v[164:167], v[188:191], v[110:113]
	v_mfma_f32_16x16x32_bf16 v[102:105], v[172:175], v[188:191], v[102:105]
	v_mfma_f32_16x16x32_bf16 v[94:97], v[164:167], v[196:199], v[94:97]
	v_mfma_f32_16x16x32_bf16 v[86:89], v[172:175], v[196:199], v[86:89]
	v_mfma_f32_16x16x32_bf16 v[78:81], v[164:167], v[204:207], v[78:81]
	v_mfma_f32_16x16x32_bf16 v[70:73], v[172:175], v[204:207], v[70:73]
	s_barrier
	s_add_u32 s50, s54, 0x20000
	ds_read_b128 v[176:179], v146 offset:16384
	ds_read_b128 v[180:183], v146 offset:17408
	ds_read_b128 v[184:187], v146 offset:18432
	ds_read_b128 v[188:191], v146 offset:19456
	ds_read_b128 v[192:195], v146 offset:20480
	ds_read_b128 v[196:199], v146 offset:21504
	ds_read_b128 v[200:203], v146 offset:22528
	ds_read_b128 v[204:207], v146 offset:23552
	s_mov_b32 m0, s58
	s_nop 0
	global_load_lds_dwordx4 v142, s[54:55]
	s_addc_u32 s51, s55, 0
	s_mov_b32 m0, s59
	s_nop 0
	global_load_lds_dwordx4 v142, s[50:51]
	s_add_u32 s50, s54, 0x40000
	s_addc_u32 s51, s55, 0
	s_mov_b32 m0, s60
	s_nop 0
	global_load_lds_dwordx4 v142, s[50:51]
	s_add_u32 s50, s54, 0x60000
	s_addc_u32 s51, s55, 0
	s_mov_b32 m0, s61
	s_nop 0
	global_load_lds_dwordx4 v142, s[50:51]
	s_add_u32 s50, s34, 0x20000
	s_mov_b32 m0, s45
	s_nop 0
	global_load_lds_dwordx4 v1, s[34:35]
	s_addc_u32 s51, s35, 0
	s_mov_b32 m0, s62
	s_nop 0
	global_load_lds_dwordx4 v1, s[50:51]
	s_waitcnt vmcnt(8)
	s_waitcnt lgkmcnt(0)
	s_barrier
	s_waitcnt lgkmcnt(7)
	v_mfma_f32_16x16x32_bf16 v[58:61], v[136:139], v[176:179], v[58:61]
	v_mfma_f32_16x16x32_bf16 v[50:53], v[152:155], v[176:179], v[50:53]
	s_waitcnt lgkmcnt(5)
	v_mfma_f32_16x16x32_bf16 v[42:45], v[136:139], v[184:187], v[42:45]
	v_mfma_f32_16x16x32_bf16 v[34:37], v[152:155], v[184:187], v[34:37]
	s_waitcnt lgkmcnt(3)
	v_mfma_f32_16x16x32_bf16 v[26:29], v[136:139], v[192:195], v[26:29]
	v_mfma_f32_16x16x32_bf16 v[18:21], v[152:155], v[192:195], v[18:21]
	s_waitcnt lgkmcnt(1)
	v_mfma_f32_16x16x32_bf16 v[10:13], v[136:139], v[200:203], v[10:13]
	v_mfma_f32_16x16x32_bf16 v[2:5], v[152:155], v[200:203], v[2:5]
	v_mfma_f32_16x16x32_bf16 v[58:61], v[148:151], v[180:183], v[58:61]
	v_mfma_f32_16x16x32_bf16 v[50:53], v[156:159], v[180:183], v[50:53]
	v_mfma_f32_16x16x32_bf16 v[42:45], v[148:151], v[188:191], v[42:45]
	v_mfma_f32_16x16x32_bf16 v[34:37], v[156:159], v[188:191], v[34:37]
	v_mfma_f32_16x16x32_bf16 v[26:29], v[148:151], v[196:199], v[26:29]
	v_mfma_f32_16x16x32_bf16 v[18:21], v[156:159], v[196:199], v[18:21]
	s_waitcnt lgkmcnt(0)
	v_mfma_f32_16x16x32_bf16 v[10:13], v[148:151], v[204:207], v[10:13]
	v_mfma_f32_16x16x32_bf16 v[2:5], v[156:159], v[204:207], v[2:5]
	v_mfma_f32_16x16x32_bf16 v[62:65], v[160:163], v[176:179], v[62:65]
	v_mfma_f32_16x16x32_bf16 v[54:57], v[168:171], v[176:179], v[54:57]
	v_mfma_f32_16x16x32_bf16 v[46:49], v[160:163], v[184:187], v[46:49]
	v_mfma_f32_16x16x32_bf16 v[38:41], v[168:171], v[184:187], v[38:41]
	v_mfma_f32_16x16x32_bf16 v[30:33], v[160:163], v[192:195], v[30:33]
	v_mfma_f32_16x16x32_bf16 v[22:25], v[168:171], v[192:195], v[22:25]
	v_mfma_f32_16x16x32_bf16 v[14:17], v[160:163], v[200:203], v[14:17]
	v_mfma_f32_16x16x32_bf16 v[6:9], v[168:171], v[200:203], v[6:9]
	v_mfma_f32_16x16x32_bf16 v[62:65], v[164:167], v[180:183], v[62:65]
	v_mfma_f32_16x16x32_bf16 v[54:57], v[172:175], v[180:183], v[54:57]
	v_mfma_f32_16x16x32_bf16 v[46:49], v[164:167], v[188:191], v[46:49]
	v_mfma_f32_16x16x32_bf16 v[38:41], v[172:175], v[188:191], v[38:41]
	v_mfma_f32_16x16x32_bf16 v[30:33], v[164:167], v[196:199], v[30:33]
	v_mfma_f32_16x16x32_bf16 v[22:25], v[172:175], v[196:199], v[22:25]
	v_mfma_f32_16x16x32_bf16 v[14:17], v[164:167], v[204:207], v[14:17]
	v_mfma_f32_16x16x32_bf16 v[6:9], v[172:175], v[204:207], v[6:9]
	s_barrier
	v_add_u32_e32 v134, 0x18000, v145
	ds_read_b128 v[136:139], v134
	ds_read_b128 v[148:151], v134 offset:1024
	ds_read_b128 v[152:155], v134 offset:2048
	ds_read_b128 v[156:159], v134 offset:3072
	v_add_u32_e32 v134, 0x1c000, v145
	ds_read_b128 v[160:163], v134
	ds_read_b128 v[164:167], v134 offset:1024
	ds_read_b128 v[168:171], v134 offset:2048
	ds_read_b128 v[172:175], v134 offset:3072
	ds_read_b128 v[176:179], v146 offset:32768
	ds_read_b128 v[180:183], v146 offset:33792
	ds_read_b128 v[184:187], v146 offset:34816
	ds_read_b128 v[188:191], v146 offset:35840
	ds_read_b128 v[192:195], v146 offset:36864
	ds_read_b128 v[196:199], v146 offset:37888
	ds_read_b128 v[200:203], v146 offset:38912
	ds_read_b128 v[204:207], v146 offset:39936
	s_add_u32 s50, s34, 0x40000
	s_addc_u32 s51, s35, 0
	s_mov_b32 m0, s63
	s_nop 0
	global_load_lds_dwordx4 v1, s[50:51]
	s_add_u32 s50, s34, 0x60000
	s_addc_u32 s51, s35, 0
	s_mov_b32 m0, s64
	s_nop 0
	global_load_lds_dwordx4 v1, s[50:51]
	s_waitcnt vmcnt(8)
	s_waitcnt lgkmcnt(0)
	s_barrier
	s_waitcnt lgkmcnt(7)
	v_mfma_f32_16x16x32_bf16 v[122:125], v[136:139], v[176:179], v[122:125]
	v_mfma_f32_16x16x32_bf16 v[114:117], v[152:155], v[176:179], v[114:117]
	s_waitcnt lgkmcnt(5)
	v_mfma_f32_16x16x32_bf16 v[106:109], v[136:139], v[184:187], v[106:109]
	v_mfma_f32_16x16x32_bf16 v[98:101], v[152:155], v[184:187], v[98:101]
	s_waitcnt lgkmcnt(3)
	v_mfma_f32_16x16x32_bf16 v[90:93], v[136:139], v[192:195], v[90:93]
	v_mfma_f32_16x16x32_bf16 v[82:85], v[152:155], v[192:195], v[82:85]
	s_waitcnt lgkmcnt(1)
	v_mfma_f32_16x16x32_bf16 v[74:77], v[136:139], v[200:203], v[74:77]
	v_mfma_f32_16x16x32_bf16 v[66:69], v[152:155], v[200:203], v[66:69]
	v_mfma_f32_16x16x32_bf16 v[122:125], v[148:151], v[180:183], v[122:125]
	v_mfma_f32_16x16x32_bf16 v[114:117], v[156:159], v[180:183], v[114:117]
	v_mfma_f32_16x16x32_bf16 v[106:109], v[148:151], v[188:191], v[106:109]
	v_mfma_f32_16x16x32_bf16 v[98:101], v[156:159], v[188:191], v[98:101]
	v_mfma_f32_16x16x32_bf16 v[90:93], v[148:151], v[196:199], v[90:93]
	v_mfma_f32_16x16x32_bf16 v[82:85], v[156:159], v[196:199], v[82:85]
	s_waitcnt lgkmcnt(0)
	v_mfma_f32_16x16x32_bf16 v[74:77], v[148:151], v[204:207], v[74:77]
	v_mfma_f32_16x16x32_bf16 v[66:69], v[156:159], v[204:207], v[66:69]
	v_mfma_f32_16x16x32_bf16 v[126:129], v[160:163], v[176:179], v[126:129]
	v_mfma_f32_16x16x32_bf16 v[118:121], v[168:171], v[176:179], v[118:121]
	v_mfma_f32_16x16x32_bf16 v[110:113], v[160:163], v[184:187], v[110:113]
	v_mfma_f32_16x16x32_bf16 v[102:105], v[168:171], v[184:187], v[102:105]
	v_mfma_f32_16x16x32_bf16 v[94:97], v[160:163], v[192:195], v[94:97]
	v_mfma_f32_16x16x32_bf16 v[86:89], v[168:171], v[192:195], v[86:89]
	v_mfma_f32_16x16x32_bf16 v[78:81], v[160:163], v[200:203], v[78:81]
	v_mfma_f32_16x16x32_bf16 v[70:73], v[168:171], v[200:203], v[70:73]
	v_mfma_f32_16x16x32_bf16 v[126:129], v[164:167], v[180:183], v[126:129]
	v_mfma_f32_16x16x32_bf16 v[118:121], v[172:175], v[180:183], v[118:121]
	v_mfma_f32_16x16x32_bf16 v[110:113], v[164:167], v[188:191], v[110:113]
	v_mfma_f32_16x16x32_bf16 v[102:105], v[172:175], v[188:191], v[102:105]
	v_mfma_f32_16x16x32_bf16 v[94:97], v[164:167], v[196:199], v[94:97]
	v_mfma_f32_16x16x32_bf16 v[86:89], v[172:175], v[196:199], v[86:89]
	v_mfma_f32_16x16x32_bf16 v[78:81], v[164:167], v[204:207], v[78:81]
	v_mfma_f32_16x16x32_bf16 v[70:73], v[172:175], v[204:207], v[70:73]
	s_barrier
	s_add_u32 s50, s54, 0x80
	s_addc_u32 s51, s55, 0
	ds_read_b128 v[176:179], v146 offset:49152
	ds_read_b128 v[180:183], v146 offset:50176
	ds_read_b128 v[184:187], v146 offset:51200
	ds_read_b128 v[188:191], v146 offset:52224
	ds_read_b128 v[192:195], v146 offset:53248
	ds_read_b128 v[196:199], v146 offset:54272
	ds_read_b128 v[200:203], v146 offset:55296
	ds_read_b128 v[204:207], v146 offset:56320
	s_mov_b32 m0, s65
	s_nop 0
	global_load_lds_dwordx4 v142, s[50:51]
	s_add_u32 s50, s54, 0x20080
	s_addc_u32 s51, s55, 0
	s_mov_b32 m0, s66
	s_nop 0
	global_load_lds_dwordx4 v142, s[50:51]
	s_add_u32 s50, s54, 0x40080
	s_addc_u32 s51, s55, 0
	s_mov_b32 m0, s74
	s_nop 0
	global_load_lds_dwordx4 v142, s[50:51]
	s_add_u32 s50, s54, 0x60080
	s_addc_u32 s51, s55, 0
	s_mov_b32 m0, s75
	s_nop 0
	global_load_lds_dwordx4 v142, s[50:51]
	s_add_u32 s34, s34, 0x20080
	s_mov_b32 m0, s67
	s_nop 0
	global_load_lds_dwordx4 v1, s[52:53]
	s_addc_u32 s35, s35, 0
	s_mov_b32 m0, s73
	s_nop 0
	global_load_lds_dwordx4 v1, s[34:35]
	s_waitcnt vmcnt(8)
	s_waitcnt lgkmcnt(0)
	s_barrier
	s_waitcnt lgkmcnt(7)
	v_mfma_f32_16x16x32_bf16 v[58:61], v[136:139], v[176:179], v[58:61]
	v_mfma_f32_16x16x32_bf16 v[50:53], v[152:155], v[176:179], v[50:53]
	s_waitcnt lgkmcnt(5)
	v_mfma_f32_16x16x32_bf16 v[42:45], v[136:139], v[184:187], v[42:45]
	v_mfma_f32_16x16x32_bf16 v[34:37], v[152:155], v[184:187], v[34:37]
	s_waitcnt lgkmcnt(3)
	v_mfma_f32_16x16x32_bf16 v[26:29], v[136:139], v[192:195], v[26:29]
	v_mfma_f32_16x16x32_bf16 v[18:21], v[152:155], v[192:195], v[18:21]
	s_waitcnt lgkmcnt(1)
	v_mfma_f32_16x16x32_bf16 v[10:13], v[136:139], v[200:203], v[10:13]
	v_mfma_f32_16x16x32_bf16 v[2:5], v[152:155], v[200:203], v[2:5]
	v_mfma_f32_16x16x32_bf16 v[58:61], v[148:151], v[180:183], v[58:61]
	v_mfma_f32_16x16x32_bf16 v[50:53], v[156:159], v[180:183], v[50:53]
	v_mfma_f32_16x16x32_bf16 v[42:45], v[148:151], v[188:191], v[42:45]
	v_mfma_f32_16x16x32_bf16 v[34:37], v[156:159], v[188:191], v[34:37]
	v_mfma_f32_16x16x32_bf16 v[26:29], v[148:151], v[196:199], v[26:29]
	v_mfma_f32_16x16x32_bf16 v[18:21], v[156:159], v[196:199], v[18:21]
	s_waitcnt lgkmcnt(0)
	v_mfma_f32_16x16x32_bf16 v[10:13], v[148:151], v[204:207], v[10:13]
	v_mfma_f32_16x16x32_bf16 v[2:5], v[156:159], v[204:207], v[2:5]
	v_mfma_f32_16x16x32_bf16 v[62:65], v[160:163], v[176:179], v[62:65]
	v_mfma_f32_16x16x32_bf16 v[54:57], v[168:171], v[176:179], v[54:57]
	v_mfma_f32_16x16x32_bf16 v[46:49], v[160:163], v[184:187], v[46:49]
	v_mfma_f32_16x16x32_bf16 v[38:41], v[168:171], v[184:187], v[38:41]
	v_mfma_f32_16x16x32_bf16 v[30:33], v[160:163], v[192:195], v[30:33]
	v_mfma_f32_16x16x32_bf16 v[22:25], v[168:171], v[192:195], v[22:25]
	v_mfma_f32_16x16x32_bf16 v[14:17], v[160:163], v[200:203], v[14:17]
	v_mfma_f32_16x16x32_bf16 v[6:9], v[168:171], v[200:203], v[6:9]
	v_mfma_f32_16x16x32_bf16 v[62:65], v[164:167], v[180:183], v[62:65]
	v_mfma_f32_16x16x32_bf16 v[54:57], v[172:175], v[180:183], v[54:57]
	v_mfma_f32_16x16x32_bf16 v[46:49], v[164:167], v[188:191], v[46:49]
	v_mfma_f32_16x16x32_bf16 v[38:41], v[172:175], v[188:191], v[38:41]
	v_mfma_f32_16x16x32_bf16 v[30:33], v[164:167], v[196:199], v[30:33]
	v_mfma_f32_16x16x32_bf16 v[22:25], v[172:175], v[196:199], v[22:25]
	v_mfma_f32_16x16x32_bf16 v[14:17], v[164:167], v[204:207], v[14:17]
	v_mfma_f32_16x16x32_bf16 v[6:9], v[172:175], v[204:207], v[6:9]
	s_barrier
	s_add_i32 s81, s81, 2
	s_add_u32 s79, s79, 0x100
	s_addc_u32 s80, s80, 0
	s_cmp_gt_u32 s81, 13
	s_mov_b64 s[50:51], s[0:1]
	s_cbranch_scc0 .LBB0_419
	s_and_b64 vcc, exec, s[24:25]
	s_cbranch_vccz .LBB0_422
	s_barrier

.LBB0_557:
	v_add_u32_e32 v134, 0x10000, v139
	ds_read_b128 v[142:145], v134
	ds_read_b128 v[146:149], v134 offset:1024
	ds_read_b128 v[150:153], v134 offset:2048
	ds_read_b128 v[154:157], v134 offset:3072
	v_add_u32_e32 v134, 0x14000, v139
	ds_read_b128 v[158:161], v134
	ds_read_b128 v[162:165], v134 offset:1024
	ds_read_b128 v[166:169], v134 offset:2048
	ds_read_b128 v[170:173], v134 offset:3072
	s_add_u32 s0, s44, 0x100
	s_addc_u32 s1, s45, 0
	s_cmp_eq_u32 s81, 12
	s_cselect_b32 s34, s15, s0
	s_cselect_b32 s35, s14, s1
	s_cselect_b32 s52, s27, s79
	s_cselect_b32 s53, s25, s80
	s_add_u32 s50, s34, 0x80
	s_addc_u32 s51, s35, 0
	ds_read_b128 v[174:177], v140
	ds_read_b128 v[178:181], v140 offset:1024
	ds_read_b128 v[182:185], v140 offset:2048
	ds_read_b128 v[186:189], v140 offset:3072
	ds_read_b128 v[190:193], v140 offset:4096
	ds_read_b128 v[194:197], v140 offset:5120
	ds_read_b128 v[198:201], v140 offset:6144
	ds_read_b128 v[202:205], v140 offset:7168
	s_add_u32 s84, s44, 0x40080
	s_addc_u32 s85, s45, 0
	s_mov_b32 m0, s74
	s_nop 0
	global_load_lds_dwordx4 v1, s[84:85]
	s_add_u32 s44, s44, 0x60080
	s_addc_u32 s45, s45, 0
	s_add_i32 s2, s43, 0xe000
	s_mov_b32 m0, s2
	s_nop 0
	global_load_lds_dwordx4 v1, s[44:45]
	s_waitcnt vmcnt(8)
	s_waitcnt lgkmcnt(0)
	s_barrier
	s_waitcnt lgkmcnt(7)
	v_mfma_f32_16x16x32_bf16 v[122:125], v[142:145], v[174:177], v[122:125]
	v_mfma_f32_16x16x32_bf16 v[114:117], v[150:153], v[174:177], v[114:117]
	s_waitcnt lgkmcnt(5)
	v_mfma_f32_16x16x32_bf16 v[106:109], v[142:145], v[182:185], v[106:109]
	v_mfma_f32_16x16x32_bf16 v[98:101], v[150:153], v[182:185], v[98:101]
	s_waitcnt lgkmcnt(3)
	v_mfma_f32_16x16x32_bf16 v[90:93], v[142:145], v[190:193], v[90:93]
	v_mfma_f32_16x16x32_bf16 v[82:85], v[150:153], v[190:193], v[82:85]
	s_waitcnt lgkmcnt(1)
	v_mfma_f32_16x16x32_bf16 v[74:77], v[142:145], v[198:201], v[74:77]
	v_mfma_f32_16x16x32_bf16 v[66:69], v[150:153], v[198:201], v[66:69]
	v_mfma_f32_16x16x32_bf16 v[122:125], v[146:149], v[178:181], v[122:125]
	v_mfma_f32_16x16x32_bf16 v[114:117], v[154:157], v[178:181], v[114:117]
	v_mfma_f32_16x16x32_bf16 v[106:109], v[146:149], v[186:189], v[106:109]
	v_mfma_f32_16x16x32_bf16 v[98:101], v[154:157], v[186:189], v[98:101]
	v_mfma_f32_16x16x32_bf16 v[90:93], v[146:149], v[194:197], v[90:93]
	v_mfma_f32_16x16x32_bf16 v[82:85], v[154:157], v[194:197], v[82:85]
	s_waitcnt lgkmcnt(0)
	v_mfma_f32_16x16x32_bf16 v[74:77], v[146:149], v[202:205], v[74:77]
	v_mfma_f32_16x16x32_bf16 v[66:69], v[154:157], v[202:205], v[66:69]
	v_mfma_f32_16x16x32_bf16 v[126:129], v[158:161], v[174:177], v[126:129]
	v_mfma_f32_16x16x32_bf16 v[118:121], v[166:169], v[174:177], v[118:121]
	v_mfma_f32_16x16x32_bf16 v[110:113], v[158:161], v[182:185], v[110:113]
	v_mfma_f32_16x16x32_bf16 v[102:105], v[166:169], v[182:185], v[102:105]
	v_mfma_f32_16x16x32_bf16 v[94:97], v[158:161], v[190:193], v[94:97]
	v_mfma_f32_16x16x32_bf16 v[86:89], v[166:169], v[190:193], v[86:89]
	v_mfma_f32_16x16x32_bf16 v[78:81], v[158:161], v[198:201], v[78:81]
	v_mfma_f32_16x16x32_bf16 v[70:73], v[166:169], v[198:201], v[70:73]
	v_mfma_f32_16x16x32_bf16 v[126:129], v[162:165], v[178:181], v[126:129]
	v_mfma_f32_16x16x32_bf16 v[118:121], v[170:173], v[178:181], v[118:121]
	v_mfma_f32_16x16x32_bf16 v[110:113], v[162:165], v[186:189], v[110:113]
	v_mfma_f32_16x16x32_bf16 v[102:105], v[170:173], v[186:189], v[102:105]
	v_mfma_f32_16x16x32_bf16 v[94:97], v[162:165], v[194:197], v[94:97]
	v_mfma_f32_16x16x32_bf16 v[86:89], v[170:173], v[194:197], v[86:89]
	v_mfma_f32_16x16x32_bf16 v[78:81], v[162:165], v[202:205], v[78:81]
	v_mfma_f32_16x16x32_bf16 v[70:73], v[170:173], v[202:205], v[70:73]
	s_barrier
	s_add_u32 s44, s52, 0x20000
	ds_read_b128 v[174:177], v140 offset:16384
	ds_read_b128 v[178:181], v140 offset:17408
	ds_read_b128 v[182:185], v140 offset:18432
	ds_read_b128 v[186:189], v140 offset:19456
	ds_read_b128 v[190:193], v140 offset:20480
	ds_read_b128 v[194:197], v140 offset:21504
	ds_read_b128 v[198:201], v140 offset:22528
	ds_read_b128 v[202:205], v140 offset:23552
	s_mov_b32 m0, s56
	s_nop 0
	global_load_lds_dwordx4 v136, s[52:53]
	s_addc_u32 s45, s53, 0
	s_mov_b32 m0, s57
	s_nop 0
	global_load_lds_dwordx4 v136, s[44:45]
	s_add_u32 s44, s52, 0x40000
	s_addc_u32 s45, s53, 0
	s_mov_b32 m0, s58
	s_nop 0
	global_load_lds_dwordx4 v136, s[44:45]
	s_add_u32 s44, s52, 0x60000
	s_addc_u32 s45, s53, 0
	s_mov_b32 m0, s59
	s_nop 0
	global_load_lds_dwordx4 v136, s[44:45]
	s_add_u32 s44, s34, 0x20000
	s_mov_b32 m0, s43
	s_nop 0
	global_load_lds_dwordx4 v1, s[34:35]
	s_addc_u32 s45, s35, 0
	s_mov_b32 m0, s60
	s_nop 0
	global_load_lds_dwordx4 v1, s[44:45]
	s_waitcnt vmcnt(8)
	s_waitcnt lgkmcnt(0)
	s_barrier
	s_waitcnt lgkmcnt(7)
	v_mfma_f32_16x16x32_bf16 v[58:61], v[142:145], v[174:177], v[58:61]
	v_mfma_f32_16x16x32_bf16 v[50:53], v[150:153], v[174:177], v[50:53]
	s_waitcnt lgkmcnt(5)
	v_mfma_f32_16x16x32_bf16 v[42:45], v[142:145], v[182:185], v[42:45]
	v_mfma_f32_16x16x32_bf16 v[34:37], v[150:153], v[182:185], v[34:37]
	s_waitcnt lgkmcnt(3)
	v_mfma_f32_16x16x32_bf16 v[26:29], v[142:145], v[190:193], v[26:29]
	v_mfma_f32_16x16x32_bf16 v[18:21], v[150:153], v[190:193], v[18:21]
	s_waitcnt lgkmcnt(1)
	v_mfma_f32_16x16x32_bf16 v[10:13], v[142:145], v[198:201], v[10:13]
	v_mfma_f32_16x16x32_bf16 v[6:9], v[150:153], v[198:201], v[6:9]
	v_mfma_f32_16x16x32_bf16 v[58:61], v[146:149], v[178:181], v[58:61]
	v_mfma_f32_16x16x32_bf16 v[50:53], v[154:157], v[178:181], v[50:53]
	v_mfma_f32_16x16x32_bf16 v[42:45], v[146:149], v[186:189], v[42:45]
	v_mfma_f32_16x16x32_bf16 v[34:37], v[154:157], v[186:189], v[34:37]
	v_mfma_f32_16x16x32_bf16 v[26:29], v[146:149], v[194:197], v[26:29]
	v_mfma_f32_16x16x32_bf16 v[18:21], v[154:157], v[194:197], v[18:21]
	s_waitcnt lgkmcnt(0)
	v_mfma_f32_16x16x32_bf16 v[10:13], v[146:149], v[202:205], v[10:13]
	v_mfma_f32_16x16x32_bf16 v[6:9], v[154:157], v[202:205], v[6:9]
	v_mfma_f32_16x16x32_bf16 v[62:65], v[158:161], v[174:177], v[62:65]
	v_mfma_f32_16x16x32_bf16 v[54:57], v[166:169], v[174:177], v[54:57]
	v_mfma_f32_16x16x32_bf16 v[46:49], v[158:161], v[182:185], v[46:49]
	v_mfma_f32_16x16x32_bf16 v[38:41], v[166:169], v[182:185], v[38:41]
	v_mfma_f32_16x16x32_bf16 v[30:33], v[158:161], v[190:193], v[30:33]
	v_mfma_f32_16x16x32_bf16 v[22:25], v[166:169], v[190:193], v[22:25]
	v_mfma_f32_16x16x32_bf16 v[14:17], v[158:161], v[198:201], v[14:17]
	v_mfma_f32_16x16x32_bf16 v[2:5], v[166:169], v[198:201], v[2:5]
	v_mfma_f32_16x16x32_bf16 v[62:65], v[162:165], v[178:181], v[62:65]
	v_mfma_f32_16x16x32_bf16 v[54:57], v[170:173], v[178:181], v[54:57]
	v_mfma_f32_16x16x32_bf16 v[46:49], v[162:165], v[186:189], v[46:49]
	v_mfma_f32_16x16x32_bf16 v[38:41], v[170:173], v[186:189], v[38:41]
	v_mfma_f32_16x16x32_bf16 v[30:33], v[162:165], v[194:197], v[30:33]
	v_mfma_f32_16x16x32_bf16 v[22:25], v[170:173], v[194:197], v[22:25]
	v_mfma_f32_16x16x32_bf16 v[14:17], v[162:165], v[202:205], v[14:17]
	v_mfma_f32_16x16x32_bf16 v[2:5], v[170:173], v[202:205], v[2:5]
	s_barrier
	v_add_u32_e32 v134, 0x18000, v139
	ds_read_b128 v[142:145], v134
	ds_read_b128 v[146:149], v134 offset:1024
	ds_read_b128 v[150:153], v134 offset:2048
	ds_read_b128 v[154:157], v134 offset:3072
	v_add_u32_e32 v134, 0x1c000, v139
	ds_read_b128 v[158:161], v134
	ds_read_b128 v[162:165], v134 offset:1024
	ds_read_b128 v[166:169], v134 offset:2048
	ds_read_b128 v[170:173], v134 offset:3072
	ds_read_b128 v[174:177], v140 offset:32768
	ds_read_b128 v[178:181], v140 offset:33792
	ds_read_b128 v[182:185], v140 offset:34816
	ds_read_b128 v[186:189], v140 offset:35840
	ds_read_b128 v[190:193], v140 offset:36864
	ds_read_b128 v[194:197], v140 offset:37888
	ds_read_b128 v[198:201], v140 offset:38912
	ds_read_b128 v[202:205], v140 offset:39936
	s_add_u32 s44, s34, 0x40000
	s_addc_u32 s45, s35, 0
	s_mov_b32 m0, s61
	s_nop 0
	global_load_lds_dwordx4 v1, s[44:45]
	s_add_u32 s44, s34, 0x60000
	s_addc_u32 s45, s35, 0
	s_mov_b32 m0, s62
	s_nop 0
	global_load_lds_dwordx4 v1, s[44:45]
	s_waitcnt vmcnt(8)
	s_waitcnt lgkmcnt(0)
	s_barrier
	s_waitcnt lgkmcnt(7)
	v_mfma_f32_16x16x32_bf16 v[122:125], v[142:145], v[174:177], v[122:125]
	v_mfma_f32_16x16x32_bf16 v[114:117], v[150:153], v[174:177], v[114:117]
	s_waitcnt lgkmcnt(5)
	v_mfma_f32_16x16x32_bf16 v[106:109], v[142:145], v[182:185], v[106:109]
	v_mfma_f32_16x16x32_bf16 v[98:101], v[150:153], v[182:185], v[98:101]
	s_waitcnt lgkmcnt(3)
	v_mfma_f32_16x16x32_bf16 v[90:93], v[142:145], v[190:193], v[90:93]
	v_mfma_f32_16x16x32_bf16 v[82:85], v[150:153], v[190:193], v[82:85]
	s_waitcnt lgkmcnt(1)
	v_mfma_f32_16x16x32_bf16 v[74:77], v[142:145], v[198:201], v[74:77]
	v_mfma_f32_16x16x32_bf16 v[66:69], v[150:153], v[198:201], v[66:69]
	v_mfma_f32_16x16x32_bf16 v[122:125], v[146:149], v[178:181], v[122:125]
	v_mfma_f32_16x16x32_bf16 v[114:117], v[154:157], v[178:181], v[114:117]
	v_mfma_f32_16x16x32_bf16 v[106:109], v[146:149], v[186:189], v[106:109]
	v_mfma_f32_16x16x32_bf16 v[98:101], v[154:157], v[186:189], v[98:101]
	v_mfma_f32_16x16x32_bf16 v[90:93], v[146:149], v[194:197], v[90:93]
	v_mfma_f32_16x16x32_bf16 v[82:85], v[154:157], v[194:197], v[82:85]
	s_waitcnt lgkmcnt(0)
	v_mfma_f32_16x16x32_bf16 v[74:77], v[146:149], v[202:205], v[74:77]
	v_mfma_f32_16x16x32_bf16 v[66:69], v[154:157], v[202:205], v[66:69]
	v_mfma_f32_16x16x32_bf16 v[126:129], v[158:161], v[174:177], v[126:129]
	v_mfma_f32_16x16x32_bf16 v[118:121], v[166:169], v[174:177], v[118:121]
	v_mfma_f32_16x16x32_bf16 v[110:113], v[158:161], v[182:185], v[110:113]
	v_mfma_f32_16x16x32_bf16 v[102:105], v[166:169], v[182:185], v[102:105]
	v_mfma_f32_16x16x32_bf16 v[94:97], v[158:161], v[190:193], v[94:97]
	v_mfma_f32_16x16x32_bf16 v[86:89], v[166:169], v[190:193], v[86:89]
	v_mfma_f32_16x16x32_bf16 v[78:81], v[158:161], v[198:201], v[78:81]
	v_mfma_f32_16x16x32_bf16 v[70:73], v[166:169], v[198:201], v[70:73]
	v_mfma_f32_16x16x32_bf16 v[126:129], v[162:165], v[178:181], v[126:129]
	v_mfma_f32_16x16x32_bf16 v[118:121], v[170:173], v[178:181], v[118:121]
	v_mfma_f32_16x16x32_bf16 v[110:113], v[162:165], v[186:189], v[110:113]
	v_mfma_f32_16x16x32_bf16 v[102:105], v[170:173], v[186:189], v[102:105]
	v_mfma_f32_16x16x32_bf16 v[94:97], v[162:165], v[194:197], v[94:97]
	v_mfma_f32_16x16x32_bf16 v[86:89], v[170:173], v[194:197], v[86:89]
	v_mfma_f32_16x16x32_bf16 v[78:81], v[162:165], v[202:205], v[78:81]
	v_mfma_f32_16x16x32_bf16 v[70:73], v[170:173], v[202:205], v[70:73]
	s_barrier
	s_add_u32 s44, s52, 0x80
	s_addc_u32 s45, s53, 0
	ds_read_b128 v[174:177], v140 offset:49152
	ds_read_b128 v[178:181], v140 offset:50176
	ds_read_b128 v[182:185], v140 offset:51200
	ds_read_b128 v[186:189], v140 offset:52224
	ds_read_b128 v[190:193], v140 offset:53248
	ds_read_b128 v[194:197], v140 offset:54272
	ds_read_b128 v[198:201], v140 offset:55296
	ds_read_b128 v[202:205], v140 offset:56320
	s_mov_b32 m0, s63
	s_nop 0
	global_load_lds_dwordx4 v136, s[44:45]
	s_add_u32 s44, s52, 0x20080
	s_addc_u32 s45, s53, 0
	s_mov_b32 m0, s64
	s_nop 0
	global_load_lds_dwordx4 v136, s[44:45]
	s_add_u32 s44, s52, 0x40080
	s_addc_u32 s45, s53, 0
	s_mov_b32 m0, s67
	s_nop 0
	global_load_lds_dwordx4 v136, s[44:45]
	s_add_u32 s44, s52, 0x60080
	s_addc_u32 s45, s53, 0
	s_mov_b32 m0, s73
	s_nop 0
	global_load_lds_dwordx4 v136, s[44:45]
	s_add_u32 s34, s34, 0x20080
	s_mov_b32 m0, s65
	s_nop 0
	global_load_lds_dwordx4 v1, s[50:51]
	s_addc_u32 s35, s35, 0
	s_mov_b32 m0, s66
	s_nop 0
	global_load_lds_dwordx4 v1, s[34:35]
	s_waitcnt vmcnt(8)
	s_waitcnt lgkmcnt(0)
	s_barrier
	s_waitcnt lgkmcnt(7)
	v_mfma_f32_16x16x32_bf16 v[58:61], v[142:145], v[174:177], v[58:61]
	v_mfma_f32_16x16x32_bf16 v[50:53], v[150:153], v[174:177], v[50:53]
	s_waitcnt lgkmcnt(5)
	v_mfma_f32_16x16x32_bf16 v[42:45], v[142:145], v[182:185], v[42:45]
	v_mfma_f32_16x16x32_bf16 v[34:37], v[150:153], v[182:185], v[34:37]
	s_waitcnt lgkmcnt(3)
	v_mfma_f32_16x16x32_bf16 v[26:29], v[142:145], v[190:193], v[26:29]
	v_mfma_f32_16x16x32_bf16 v[18:21], v[150:153], v[190:193], v[18:21]
	s_waitcnt lgkmcnt(1)
	v_mfma_f32_16x16x32_bf16 v[10:13], v[142:145], v[198:201], v[10:13]
	v_mfma_f32_16x16x32_bf16 v[6:9], v[150:153], v[198:201], v[6:9]
	v_mfma_f32_16x16x32_bf16 v[58:61], v[146:149], v[178:181], v[58:61]
	v_mfma_f32_16x16x32_bf16 v[50:53], v[154:157], v[178:181], v[50:53]
	v_mfma_f32_16x16x32_bf16 v[42:45], v[146:149], v[186:189], v[42:45]
	v_mfma_f32_16x16x32_bf16 v[34:37], v[154:157], v[186:189], v[34:37]
	v_mfma_f32_16x16x32_bf16 v[26:29], v[146:149], v[194:197], v[26:29]
	v_mfma_f32_16x16x32_bf16 v[18:21], v[154:157], v[194:197], v[18:21]
	s_waitcnt lgkmcnt(0)
	v_mfma_f32_16x16x32_bf16 v[10:13], v[146:149], v[202:205], v[10:13]
	v_mfma_f32_16x16x32_bf16 v[6:9], v[154:157], v[202:205], v[6:9]
	v_mfma_f32_16x16x32_bf16 v[62:65], v[158:161], v[174:177], v[62:65]
	v_mfma_f32_16x16x32_bf16 v[54:57], v[166:169], v[174:177], v[54:57]
	v_mfma_f32_16x16x32_bf16 v[46:49], v[158:161], v[182:185], v[46:49]
	v_mfma_f32_16x16x32_bf16 v[38:41], v[166:169], v[182:185], v[38:41]
	v_mfma_f32_16x16x32_bf16 v[30:33], v[158:161], v[190:193], v[30:33]
	v_mfma_f32_16x16x32_bf16 v[22:25], v[166:169], v[190:193], v[22:25]
	v_mfma_f32_16x16x32_bf16 v[14:17], v[158:161], v[198:201], v[14:17]
	v_mfma_f32_16x16x32_bf16 v[2:5], v[166:169], v[198:201], v[2:5]
	v_mfma_f32_16x16x32_bf16 v[62:65], v[162:165], v[178:181], v[62:65]
	v_mfma_f32_16x16x32_bf16 v[54:57], v[170:173], v[178:181], v[54:57]
	v_mfma_f32_16x16x32_bf16 v[46:49], v[162:165], v[186:189], v[46:49]
	v_mfma_f32_16x16x32_bf16 v[38:41], v[170:173], v[186:189], v[38:41]
	v_mfma_f32_16x16x32_bf16 v[30:33], v[162:165], v[194:197], v[30:33]
	v_mfma_f32_16x16x32_bf16 v[22:25], v[170:173], v[194:197], v[22:25]
	v_mfma_f32_16x16x32_bf16 v[14:17], v[162:165], v[202:205], v[14:17]
	v_mfma_f32_16x16x32_bf16 v[2:5], v[170:173], v[202:205], v[2:5]
	s_barrier
	s_add_i32 s81, s81, 2
	s_add_u32 s79, s79, 0x100
	s_addc_u32 s80, s80, 0
	s_cmp_gt_u32 s81, 13
	s_mov_b64 s[44:45], s[0:1]
	s_cbranch_scc0 .LBB0_557
	s_and_b64 vcc, exec, s[10:11]
	s_cbranch_vccz .LBB0_560
	s_barrier

.LBB0_752:
	v_add_u32_e32 v138, 0x10000, v143
	ds_read_b128 v[130:133], v138
	ds_read_b128 v[154:157], v138 offset:1024
	ds_read_b128 v[158:161], v138 offset:2048
	ds_read_b128 v[162:165], v138 offset:3072
	v_add_u32_e32 v138, 0x14000, v143
	ds_read_b128 v[166:169], v138
	ds_read_b128 v[170:173], v138 offset:1024
	ds_read_b128 v[174:177], v138 offset:2048
	ds_read_b128 v[178:181], v138 offset:3072
	s_add_u32 s0, s44, 0x100
	s_addc_u32 s1, s45, 0
	s_cmp_eq_u32 vcc_lo, 12
	s_cselect_b32 s34, s9, s0
	s_cselect_b32 s35, s7, s1
	s_cselect_b32 s52, s15, s27
	s_cselect_b32 s53, s14, s37
	s_add_u32 s50, s34, 0x80
	s_addc_u32 s51, s35, 0
	ds_read_b128 v[182:185], v145
	ds_read_b128 v[186:189], v145 offset:1024
	ds_read_b128 v[190:193], v145 offset:2048
	ds_read_b128 v[194:197], v145 offset:3072
	ds_read_b128 v[198:201], v145 offset:4096
	ds_read_b128 v[202:205], v145 offset:5120
	ds_read_b128 v[206:209], v145 offset:6144
	ds_read_b128 v[210:213], v145 offset:7168
	s_add_u32 s2, s44, 0x40080
	s_addc_u32 s3, s45, 0
	s_mov_b32 m0, s96
	s_nop 0
	global_load_lds_dwordx4 v1, s[2:3]
	s_add_u32 s2, s44, 0x60080
	s_addc_u32 s3, s45, 0
	s_add_i32 s12, s58, 0xe000
	s_mov_b32 m0, s12
	s_nop 0
	global_load_lds_dwordx4 v1, s[2:3]
	s_waitcnt vmcnt(8)
	s_waitcnt lgkmcnt(0)
	s_barrier
	s_waitcnt lgkmcnt(7)
	v_mfma_f32_16x16x32_bf16 v[118:121], v[130:133], v[182:185], v[118:121]
	v_mfma_f32_16x16x32_bf16 v[114:117], v[158:161], v[182:185], v[114:117]
	s_waitcnt lgkmcnt(5)
	v_mfma_f32_16x16x32_bf16 v[102:105], v[130:133], v[190:193], v[102:105]
	v_mfma_f32_16x16x32_bf16 v[98:101], v[158:161], v[190:193], v[98:101]
	s_waitcnt lgkmcnt(3)
	v_mfma_f32_16x16x32_bf16 v[86:89], v[130:133], v[198:201], v[86:89]
	v_mfma_f32_16x16x32_bf16 v[82:85], v[158:161], v[198:201], v[82:85]
	s_waitcnt lgkmcnt(1)
	v_mfma_f32_16x16x32_bf16 v[70:73], v[130:133], v[206:209], v[70:73]
	v_mfma_f32_16x16x32_bf16 v[66:69], v[158:161], v[206:209], v[66:69]
	v_mfma_f32_16x16x32_bf16 v[118:121], v[154:157], v[186:189], v[118:121]
	v_mfma_f32_16x16x32_bf16 v[114:117], v[162:165], v[186:189], v[114:117]
	v_mfma_f32_16x16x32_bf16 v[102:105], v[154:157], v[194:197], v[102:105]
	v_mfma_f32_16x16x32_bf16 v[98:101], v[162:165], v[194:197], v[98:101]
	v_mfma_f32_16x16x32_bf16 v[86:89], v[154:157], v[202:205], v[86:89]
	v_mfma_f32_16x16x32_bf16 v[82:85], v[162:165], v[202:205], v[82:85]
	s_waitcnt lgkmcnt(0)
	v_mfma_f32_16x16x32_bf16 v[70:73], v[154:157], v[210:213], v[70:73]
	v_mfma_f32_16x16x32_bf16 v[66:69], v[162:165], v[210:213], v[66:69]
	v_mfma_f32_16x16x32_bf16 v[126:129], v[166:169], v[182:185], v[126:129]
	v_mfma_f32_16x16x32_bf16 v[122:125], v[174:177], v[182:185], v[122:125]
	v_mfma_f32_16x16x32_bf16 v[110:113], v[166:169], v[190:193], v[110:113]
	v_mfma_f32_16x16x32_bf16 v[106:109], v[174:177], v[190:193], v[106:109]
	v_mfma_f32_16x16x32_bf16 v[94:97], v[166:169], v[198:201], v[94:97]
	v_mfma_f32_16x16x32_bf16 v[90:93], v[174:177], v[198:201], v[90:93]
	v_mfma_f32_16x16x32_bf16 v[78:81], v[166:169], v[206:209], v[78:81]
	v_mfma_f32_16x16x32_bf16 v[74:77], v[174:177], v[206:209], v[74:77]
	v_mfma_f32_16x16x32_bf16 v[126:129], v[170:173], v[186:189], v[126:129]
	v_mfma_f32_16x16x32_bf16 v[122:125], v[178:181], v[186:189], v[122:125]
	v_mfma_f32_16x16x32_bf16 v[110:113], v[170:173], v[194:197], v[110:113]
	v_mfma_f32_16x16x32_bf16 v[106:109], v[178:181], v[194:197], v[106:109]
	v_mfma_f32_16x16x32_bf16 v[94:97], v[170:173], v[202:205], v[94:97]
	v_mfma_f32_16x16x32_bf16 v[90:93], v[178:181], v[202:205], v[90:93]
	v_mfma_f32_16x16x32_bf16 v[78:81], v[170:173], v[210:213], v[78:81]
	v_mfma_f32_16x16x32_bf16 v[74:77], v[178:181], v[210:213], v[74:77]
	s_barrier
	ds_read_b128 v[182:185], v145 offset:16384
	ds_read_b128 v[186:189], v145 offset:17408
	ds_read_b128 v[190:193], v145 offset:18432
	ds_read_b128 v[194:197], v145 offset:19456
	ds_read_b128 v[198:201], v145 offset:20480
	ds_read_b128 v[202:205], v145 offset:21504
	ds_read_b128 v[206:209], v145 offset:22528
	ds_read_b128 v[210:213], v145 offset:23552
	s_mov_b32 m0, s60
	s_nop 0
	global_load_lds_dwordx4 v135, s[52:53]
	s_add_u32 s2, s52, 0x20000
	s_addc_u32 s3, s53, 0
	s_mov_b32 m0, s61
	s_nop 0
	global_load_lds_dwordx4 v135, s[2:3]
	s_add_u32 s2, s52, 0x40000
	s_addc_u32 s3, s53, 0
	s_mov_b32 m0, s62
	s_nop 0
	global_load_lds_dwordx4 v135, s[2:3]
	s_add_u32 s2, s52, 0x60000
	s_addc_u32 s3, s53, 0
	s_mov_b32 m0, s63
	s_nop 0
	global_load_lds_dwordx4 v135, s[2:3]
	s_mov_b32 m0, s58
	s_nop 0
	global_load_lds_dwordx4 v1, s[34:35]
	s_add_u32 s2, s34, 0x20000
	s_addc_u32 s3, s35, 0
	s_mov_b32 m0, s64
	s_nop 0
	global_load_lds_dwordx4 v1, s[2:3]
	s_waitcnt vmcnt(8)
	s_waitcnt lgkmcnt(0)
	s_barrier
	s_waitcnt lgkmcnt(7)
	v_mfma_f32_16x16x32_bf16 v[54:57], v[130:133], v[182:185], v[54:57]
	v_mfma_f32_16x16x32_bf16 v[50:53], v[158:161], v[182:185], v[50:53]
	s_waitcnt lgkmcnt(5)
	v_mfma_f32_16x16x32_bf16 v[38:41], v[130:133], v[190:193], v[38:41]
	v_mfma_f32_16x16x32_bf16 v[34:37], v[158:161], v[190:193], v[34:37]
	s_waitcnt lgkmcnt(3)
	v_mfma_f32_16x16x32_bf16 v[22:25], v[130:133], v[198:201], v[22:25]
	v_mfma_f32_16x16x32_bf16 v[18:21], v[158:161], v[198:201], v[18:21]
	s_waitcnt lgkmcnt(1)
	v_mfma_f32_16x16x32_bf16 v[10:13], v[130:133], v[206:209], v[10:13]
	v_mfma_f32_16x16x32_bf16 v[6:9], v[158:161], v[206:209], v[6:9]
	v_mfma_f32_16x16x32_bf16 v[54:57], v[154:157], v[186:189], v[54:57]
	v_mfma_f32_16x16x32_bf16 v[50:53], v[162:165], v[186:189], v[50:53]
	v_mfma_f32_16x16x32_bf16 v[38:41], v[154:157], v[194:197], v[38:41]
	v_mfma_f32_16x16x32_bf16 v[34:37], v[162:165], v[194:197], v[34:37]
	v_mfma_f32_16x16x32_bf16 v[22:25], v[154:157], v[202:205], v[22:25]
	v_mfma_f32_16x16x32_bf16 v[18:21], v[162:165], v[202:205], v[18:21]
	s_waitcnt lgkmcnt(0)
	v_mfma_f32_16x16x32_bf16 v[10:13], v[154:157], v[210:213], v[10:13]
	v_mfma_f32_16x16x32_bf16 v[6:9], v[162:165], v[210:213], v[6:9]
	v_mfma_f32_16x16x32_bf16 v[62:65], v[166:169], v[182:185], v[62:65]
	v_mfma_f32_16x16x32_bf16 v[58:61], v[174:177], v[182:185], v[58:61]
	v_mfma_f32_16x16x32_bf16 v[46:49], v[166:169], v[190:193], v[46:49]
	v_mfma_f32_16x16x32_bf16 v[42:45], v[174:177], v[190:193], v[42:45]
	v_mfma_f32_16x16x32_bf16 v[30:33], v[166:169], v[198:201], v[30:33]
	v_mfma_f32_16x16x32_bf16 v[26:29], v[174:177], v[198:201], v[26:29]
	v_mfma_f32_16x16x32_bf16 v[14:17], v[166:169], v[206:209], v[14:17]
	v_mfma_f32_16x16x32_bf16 v[2:5], v[174:177], v[206:209], v[2:5]
	v_mfma_f32_16x16x32_bf16 v[62:65], v[170:173], v[186:189], v[62:65]
	v_mfma_f32_16x16x32_bf16 v[58:61], v[178:181], v[186:189], v[58:61]
	v_mfma_f32_16x16x32_bf16 v[46:49], v[170:173], v[194:197], v[46:49]
	v_mfma_f32_16x16x32_bf16 v[42:45], v[178:181], v[194:197], v[42:45]
	v_mfma_f32_16x16x32_bf16 v[30:33], v[170:173], v[202:205], v[30:33]
	v_mfma_f32_16x16x32_bf16 v[26:29], v[178:181], v[202:205], v[26:29]
	v_mfma_f32_16x16x32_bf16 v[14:17], v[170:173], v[210:213], v[14:17]
	v_mfma_f32_16x16x32_bf16 v[2:5], v[178:181], v[210:213], v[2:5]
	s_barrier
	v_add_u32_e32 v138, 0x18000, v143
	ds_read_b128 v[130:133], v138
	ds_read_b128 v[154:157], v138 offset:1024
	ds_read_b128 v[158:161], v138 offset:2048
	ds_read_b128 v[162:165], v138 offset:3072
	v_add_u32_e32 v138, 0x1c000, v143
	ds_read_b128 v[166:169], v138
	ds_read_b128 v[170:173], v138 offset:1024
	ds_read_b128 v[174:177], v138 offset:2048
	ds_read_b128 v[178:181], v138 offset:3072
	ds_read_b128 v[182:185], v145 offset:32768
	ds_read_b128 v[186:189], v145 offset:33792
	ds_read_b128 v[190:193], v145 offset:34816
	ds_read_b128 v[194:197], v145 offset:35840
	ds_read_b128 v[198:201], v145 offset:36864
	ds_read_b128 v[202:205], v145 offset:37888
	ds_read_b128 v[206:209], v145 offset:38912
	ds_read_b128 v[210:213], v145 offset:39936
	s_add_u32 s2, s34, 0x40000
	s_addc_u32 s3, s35, 0
	s_mov_b32 m0, s65
	s_nop 0
	global_load_lds_dwordx4 v1, s[2:3]
	s_add_u32 s2, s34, 0x60000
	s_addc_u32 s3, s35, 0
	s_mov_b32 m0, s66
	s_nop 0
	global_load_lds_dwordx4 v1, s[2:3]
	s_waitcnt vmcnt(8)
	s_waitcnt lgkmcnt(0)
	s_barrier
	s_waitcnt lgkmcnt(7)
	v_mfma_f32_16x16x32_bf16 v[118:121], v[130:133], v[182:185], v[118:121]
	v_mfma_f32_16x16x32_bf16 v[114:117], v[158:161], v[182:185], v[114:117]
	s_waitcnt lgkmcnt(5)
	v_mfma_f32_16x16x32_bf16 v[102:105], v[130:133], v[190:193], v[102:105]
	v_mfma_f32_16x16x32_bf16 v[98:101], v[158:161], v[190:193], v[98:101]
	s_waitcnt lgkmcnt(3)
	v_mfma_f32_16x16x32_bf16 v[86:89], v[130:133], v[198:201], v[86:89]
	v_mfma_f32_16x16x32_bf16 v[82:85], v[158:161], v[198:201], v[82:85]
	s_waitcnt lgkmcnt(1)
	v_mfma_f32_16x16x32_bf16 v[70:73], v[130:133], v[206:209], v[70:73]
	v_mfma_f32_16x16x32_bf16 v[66:69], v[158:161], v[206:209], v[66:69]
	v_mfma_f32_16x16x32_bf16 v[118:121], v[154:157], v[186:189], v[118:121]
	v_mfma_f32_16x16x32_bf16 v[114:117], v[162:165], v[186:189], v[114:117]
	v_mfma_f32_16x16x32_bf16 v[102:105], v[154:157], v[194:197], v[102:105]
	v_mfma_f32_16x16x32_bf16 v[98:101], v[162:165], v[194:197], v[98:101]
	v_mfma_f32_16x16x32_bf16 v[86:89], v[154:157], v[202:205], v[86:89]
	v_mfma_f32_16x16x32_bf16 v[82:85], v[162:165], v[202:205], v[82:85]
	s_waitcnt lgkmcnt(0)
	v_mfma_f32_16x16x32_bf16 v[70:73], v[154:157], v[210:213], v[70:73]
	v_mfma_f32_16x16x32_bf16 v[66:69], v[162:165], v[210:213], v[66:69]
	v_mfma_f32_16x16x32_bf16 v[126:129], v[166:169], v[182:185], v[126:129]
	v_mfma_f32_16x16x32_bf16 v[122:125], v[174:177], v[182:185], v[122:125]
	v_mfma_f32_16x16x32_bf16 v[110:113], v[166:169], v[190:193], v[110:113]
	v_mfma_f32_16x16x32_bf16 v[106:109], v[174:177], v[190:193], v[106:109]
	v_mfma_f32_16x16x32_bf16 v[94:97], v[166:169], v[198:201], v[94:97]
	v_mfma_f32_16x16x32_bf16 v[90:93], v[174:177], v[198:201], v[90:93]
	v_mfma_f32_16x16x32_bf16 v[78:81], v[166:169], v[206:209], v[78:81]
	v_mfma_f32_16x16x32_bf16 v[74:77], v[174:177], v[206:209], v[74:77]
	v_mfma_f32_16x16x32_bf16 v[126:129], v[170:173], v[186:189], v[126:129]
	v_mfma_f32_16x16x32_bf16 v[122:125], v[178:181], v[186:189], v[122:125]
	v_mfma_f32_16x16x32_bf16 v[110:113], v[170:173], v[194:197], v[110:113]
	v_mfma_f32_16x16x32_bf16 v[106:109], v[178:181], v[194:197], v[106:109]
	v_mfma_f32_16x16x32_bf16 v[94:97], v[170:173], v[202:205], v[94:97]
	v_mfma_f32_16x16x32_bf16 v[90:93], v[178:181], v[202:205], v[90:93]
	v_mfma_f32_16x16x32_bf16 v[78:81], v[170:173], v[210:213], v[78:81]
	v_mfma_f32_16x16x32_bf16 v[74:77], v[178:181], v[210:213], v[74:77]
	s_barrier
	s_add_u32 s2, s52, 0x80
	s_addc_u32 s3, s53, 0
	ds_read_b128 v[182:185], v145 offset:49152
	ds_read_b128 v[186:189], v145 offset:50176
	ds_read_b128 v[190:193], v145 offset:51200
	ds_read_b128 v[194:197], v145 offset:52224
	ds_read_b128 v[198:201], v145 offset:53248
	ds_read_b128 v[202:205], v145 offset:54272
	ds_read_b128 v[206:209], v145 offset:55296
	ds_read_b128 v[210:213], v145 offset:56320
	s_mov_b32 m0, s90
	s_nop 0
	global_load_lds_dwordx4 v135, s[2:3]
	s_add_u32 s2, s52, 0x20080
	s_addc_u32 s3, s53, 0
	s_mov_b32 m0, s91
	s_nop 0
	global_load_lds_dwordx4 v135, s[2:3]
	s_add_u32 s2, s52, 0x40080
	s_addc_u32 s3, s53, 0
	s_mov_b32 m0, s94
	s_nop 0
	global_load_lds_dwordx4 v135, s[2:3]
	s_add_u32 s2, s52, 0x60080
	s_addc_u32 s3, s53, 0
	s_mov_b32 m0, s95
	s_nop 0
	global_load_lds_dwordx4 v135, s[2:3]
	s_mov_b32 m0, s92
	s_nop 0
	global_load_lds_dwordx4 v1, s[50:51]
	s_add_u32 s2, s34, 0x20080
	s_addc_u32 s3, s35, 0
	s_mov_b32 m0, s93
	s_nop 0
	global_load_lds_dwordx4 v1, s[2:3]
	s_waitcnt vmcnt(8)
	s_waitcnt lgkmcnt(0)
	s_barrier
	s_waitcnt lgkmcnt(7)
	v_mfma_f32_16x16x32_bf16 v[54:57], v[130:133], v[182:185], v[54:57]
	v_mfma_f32_16x16x32_bf16 v[50:53], v[158:161], v[182:185], v[50:53]
	s_waitcnt lgkmcnt(5)
	v_mfma_f32_16x16x32_bf16 v[38:41], v[130:133], v[190:193], v[38:41]
	v_mfma_f32_16x16x32_bf16 v[34:37], v[158:161], v[190:193], v[34:37]
	s_waitcnt lgkmcnt(3)
	v_mfma_f32_16x16x32_bf16 v[22:25], v[130:133], v[198:201], v[22:25]
	v_mfma_f32_16x16x32_bf16 v[18:21], v[158:161], v[198:201], v[18:21]
	s_waitcnt lgkmcnt(1)
	v_mfma_f32_16x16x32_bf16 v[10:13], v[130:133], v[206:209], v[10:13]
	v_mfma_f32_16x16x32_bf16 v[6:9], v[158:161], v[206:209], v[6:9]
	v_mfma_f32_16x16x32_bf16 v[54:57], v[154:157], v[186:189], v[54:57]
	v_mfma_f32_16x16x32_bf16 v[50:53], v[162:165], v[186:189], v[50:53]
	v_mfma_f32_16x16x32_bf16 v[38:41], v[154:157], v[194:197], v[38:41]
	v_mfma_f32_16x16x32_bf16 v[34:37], v[162:165], v[194:197], v[34:37]
	v_mfma_f32_16x16x32_bf16 v[22:25], v[154:157], v[202:205], v[22:25]
	v_mfma_f32_16x16x32_bf16 v[18:21], v[162:165], v[202:205], v[18:21]
	s_waitcnt lgkmcnt(0)
	v_mfma_f32_16x16x32_bf16 v[10:13], v[154:157], v[210:213], v[10:13]
	v_mfma_f32_16x16x32_bf16 v[6:9], v[162:165], v[210:213], v[6:9]
	v_mfma_f32_16x16x32_bf16 v[62:65], v[166:169], v[182:185], v[62:65]
	v_mfma_f32_16x16x32_bf16 v[58:61], v[174:177], v[182:185], v[58:61]
	v_mfma_f32_16x16x32_bf16 v[46:49], v[166:169], v[190:193], v[46:49]
	v_mfma_f32_16x16x32_bf16 v[42:45], v[174:177], v[190:193], v[42:45]
	v_mfma_f32_16x16x32_bf16 v[30:33], v[166:169], v[198:201], v[30:33]
	v_mfma_f32_16x16x32_bf16 v[26:29], v[174:177], v[198:201], v[26:29]
	v_mfma_f32_16x16x32_bf16 v[14:17], v[166:169], v[206:209], v[14:17]
	v_mfma_f32_16x16x32_bf16 v[2:5], v[174:177], v[206:209], v[2:5]
	v_mfma_f32_16x16x32_bf16 v[62:65], v[170:173], v[186:189], v[62:65]
	v_mfma_f32_16x16x32_bf16 v[58:61], v[178:181], v[186:189], v[58:61]
	v_mfma_f32_16x16x32_bf16 v[46:49], v[170:173], v[194:197], v[46:49]
	v_mfma_f32_16x16x32_bf16 v[42:45], v[178:181], v[194:197], v[42:45]
	v_mfma_f32_16x16x32_bf16 v[30:33], v[170:173], v[202:205], v[30:33]
	v_mfma_f32_16x16x32_bf16 v[26:29], v[178:181], v[202:205], v[26:29]
	v_mfma_f32_16x16x32_bf16 v[14:17], v[170:173], v[210:213], v[14:17]
	v_mfma_f32_16x16x32_bf16 v[2:5], v[178:181], v[210:213], v[2:5]
	s_barrier
	s_add_i32 vcc_lo, vcc_lo, 2
	s_add_u32 s27, s27, 0x100
	s_addc_u32 s37, s37, 0
	s_cmp_gt_u32 vcc_lo, 13
	s_mov_b64 s[44:45], s[0:1]
	s_cbranch_scc0 .LBB0_752
	s_and_b64 vcc, exec, s[24:25]
	s_cbranch_vccz .LBB0_755
	s_barrier

.LBB0_800:
	v_add_u32_e32 v134, 0x10000, v139
	ds_read_b128 v[142:145], v134
	ds_read_b128 v[146:149], v134 offset:1024
	ds_read_b128 v[150:153], v134 offset:2048
	ds_read_b128 v[154:157], v134 offset:3072
	v_add_u32_e32 v134, 0x14000, v139
	ds_read_b128 v[158:161], v134
	ds_read_b128 v[162:165], v134 offset:1024
	ds_read_b128 v[166:169], v134 offset:2048
	ds_read_b128 v[170:173], v134 offset:3072
	s_add_u32 s0, s42, 0x100
	s_addc_u32 s1, s43, 0
	s_cmp_eq_u32 s88, 12
	s_cselect_b32 s34, s15, s0
	s_cselect_b32 s35, s14, s1
	s_cselect_b32 s50, s25, s86
	s_cselect_b32 s51, s11, s87
	s_add_u32 s44, s34, 0x80
	s_addc_u32 s45, s35, 0
	ds_read_b128 v[174:177], v140
	ds_read_b128 v[178:181], v140 offset:1024
	ds_read_b128 v[182:185], v140 offset:2048
	ds_read_b128 v[186:189], v140 offset:3072
	ds_read_b128 v[190:193], v140 offset:4096
	ds_read_b128 v[194:197], v140 offset:5120
	ds_read_b128 v[198:201], v140 offset:6144
	ds_read_b128 v[202:205], v140 offset:7168
	s_add_u32 s2, s42, 0x40080
	s_addc_u32 s3, s43, 0
	s_mov_b32 m0, s67
	s_nop 0
	global_load_lds_dwordx4 v1, s[2:3]
	s_add_u32 s2, s42, 0x60080
	s_addc_u32 s3, s43, 0
	s_add_i32 s12, s39, 0xe000
	s_mov_b32 m0, s12
	s_nop 0
	global_load_lds_dwordx4 v1, s[2:3]
	s_waitcnt vmcnt(8)
	s_waitcnt lgkmcnt(0)
	s_barrier
	s_waitcnt lgkmcnt(7)
	v_mfma_f32_16x16x32_bf16 v[122:125], v[142:145], v[174:177], v[122:125]
	v_mfma_f32_16x16x32_bf16 v[114:117], v[150:153], v[174:177], v[114:117]
	s_waitcnt lgkmcnt(5)
	v_mfma_f32_16x16x32_bf16 v[106:109], v[142:145], v[182:185], v[106:109]
	v_mfma_f32_16x16x32_bf16 v[98:101], v[150:153], v[182:185], v[98:101]
	s_waitcnt lgkmcnt(3)
	v_mfma_f32_16x16x32_bf16 v[90:93], v[142:145], v[190:193], v[90:93]
	v_mfma_f32_16x16x32_bf16 v[82:85], v[150:153], v[190:193], v[82:85]
	s_waitcnt lgkmcnt(1)
	v_mfma_f32_16x16x32_bf16 v[74:77], v[142:145], v[198:201], v[74:77]
	v_mfma_f32_16x16x32_bf16 v[66:69], v[150:153], v[198:201], v[66:69]
	v_mfma_f32_16x16x32_bf16 v[122:125], v[146:149], v[178:181], v[122:125]
	v_mfma_f32_16x16x32_bf16 v[114:117], v[154:157], v[178:181], v[114:117]
	v_mfma_f32_16x16x32_bf16 v[106:109], v[146:149], v[186:189], v[106:109]
	v_mfma_f32_16x16x32_bf16 v[98:101], v[154:157], v[186:189], v[98:101]
	v_mfma_f32_16x16x32_bf16 v[90:93], v[146:149], v[194:197], v[90:93]
	v_mfma_f32_16x16x32_bf16 v[82:85], v[154:157], v[194:197], v[82:85]
	s_waitcnt lgkmcnt(0)
	v_mfma_f32_16x16x32_bf16 v[74:77], v[146:149], v[202:205], v[74:77]
	v_mfma_f32_16x16x32_bf16 v[66:69], v[154:157], v[202:205], v[66:69]
	v_mfma_f32_16x16x32_bf16 v[126:129], v[158:161], v[174:177], v[126:129]
	v_mfma_f32_16x16x32_bf16 v[118:121], v[166:169], v[174:177], v[118:121]
	v_mfma_f32_16x16x32_bf16 v[110:113], v[158:161], v[182:185], v[110:113]
	v_mfma_f32_16x16x32_bf16 v[102:105], v[166:169], v[182:185], v[102:105]
	v_mfma_f32_16x16x32_bf16 v[94:97], v[158:161], v[190:193], v[94:97]
	v_mfma_f32_16x16x32_bf16 v[86:89], v[166:169], v[190:193], v[86:89]
	v_mfma_f32_16x16x32_bf16 v[78:81], v[158:161], v[198:201], v[78:81]
	v_mfma_f32_16x16x32_bf16 v[70:73], v[166:169], v[198:201], v[70:73]
	v_mfma_f32_16x16x32_bf16 v[126:129], v[162:165], v[178:181], v[126:129]
	v_mfma_f32_16x16x32_bf16 v[118:121], v[170:173], v[178:181], v[118:121]
	v_mfma_f32_16x16x32_bf16 v[110:113], v[162:165], v[186:189], v[110:113]
	v_mfma_f32_16x16x32_bf16 v[102:105], v[170:173], v[186:189], v[102:105]
	v_mfma_f32_16x16x32_bf16 v[94:97], v[162:165], v[194:197], v[94:97]
	v_mfma_f32_16x16x32_bf16 v[86:89], v[170:173], v[194:197], v[86:89]
	v_mfma_f32_16x16x32_bf16 v[78:81], v[162:165], v[202:205], v[78:81]
	v_mfma_f32_16x16x32_bf16 v[70:73], v[170:173], v[202:205], v[70:73]
	s_barrier
	ds_read_b128 v[174:177], v140 offset:16384
	ds_read_b128 v[178:181], v140 offset:17408
	ds_read_b128 v[182:185], v140 offset:18432
	ds_read_b128 v[186:189], v140 offset:19456
	ds_read_b128 v[190:193], v140 offset:20480
	ds_read_b128 v[194:197], v140 offset:21504
	ds_read_b128 v[198:201], v140 offset:22528
	ds_read_b128 v[202:205], v140 offset:23552
	s_mov_b32 m0, s54
	s_nop 0
	global_load_lds_dwordx4 v136, s[50:51]
	s_add_u32 s2, s50, 0x20000
	s_addc_u32 s3, s51, 0
	s_mov_b32 m0, s55
	s_nop 0
	global_load_lds_dwordx4 v136, s[2:3]
	s_add_u32 s2, s50, 0x40000
	s_addc_u32 s3, s51, 0
	s_mov_b32 m0, s56
	s_nop 0
	global_load_lds_dwordx4 v136, s[2:3]
	s_add_u32 s2, s50, 0x60000
	s_addc_u32 s3, s51, 0
	s_mov_b32 m0, s57
	s_nop 0
	global_load_lds_dwordx4 v136, s[2:3]
	s_mov_b32 m0, s39
	s_nop 0
	global_load_lds_dwordx4 v1, s[34:35]
	s_add_u32 s2, s34, 0x20000
	s_addc_u32 s3, s35, 0
	s_mov_b32 m0, s58
	s_nop 0
	global_load_lds_dwordx4 v1, s[2:3]
	s_waitcnt vmcnt(8)
	s_waitcnt lgkmcnt(0)
	s_barrier
	s_waitcnt lgkmcnt(7)
	v_mfma_f32_16x16x32_bf16 v[58:61], v[142:145], v[174:177], v[58:61]
	v_mfma_f32_16x16x32_bf16 v[50:53], v[150:153], v[174:177], v[50:53]
	s_waitcnt lgkmcnt(5)
	v_mfma_f32_16x16x32_bf16 v[42:45], v[142:145], v[182:185], v[42:45]
	v_mfma_f32_16x16x32_bf16 v[34:37], v[150:153], v[182:185], v[34:37]
	s_waitcnt lgkmcnt(3)
	v_mfma_f32_16x16x32_bf16 v[26:29], v[142:145], v[190:193], v[26:29]
	v_mfma_f32_16x16x32_bf16 v[18:21], v[150:153], v[190:193], v[18:21]
	s_waitcnt lgkmcnt(1)
	v_mfma_f32_16x16x32_bf16 v[10:13], v[142:145], v[198:201], v[10:13]
	v_mfma_f32_16x16x32_bf16 v[6:9], v[150:153], v[198:201], v[6:9]
	v_mfma_f32_16x16x32_bf16 v[58:61], v[146:149], v[178:181], v[58:61]
	v_mfma_f32_16x16x32_bf16 v[50:53], v[154:157], v[178:181], v[50:53]
	v_mfma_f32_16x16x32_bf16 v[42:45], v[146:149], v[186:189], v[42:45]
	v_mfma_f32_16x16x32_bf16 v[34:37], v[154:157], v[186:189], v[34:37]
	v_mfma_f32_16x16x32_bf16 v[26:29], v[146:149], v[194:197], v[26:29]
	v_mfma_f32_16x16x32_bf16 v[18:21], v[154:157], v[194:197], v[18:21]
	s_waitcnt lgkmcnt(0)
	v_mfma_f32_16x16x32_bf16 v[10:13], v[146:149], v[202:205], v[10:13]
	v_mfma_f32_16x16x32_bf16 v[6:9], v[154:157], v[202:205], v[6:9]
	v_mfma_f32_16x16x32_bf16 v[62:65], v[158:161], v[174:177], v[62:65]
	v_mfma_f32_16x16x32_bf16 v[54:57], v[166:169], v[174:177], v[54:57]
	v_mfma_f32_16x16x32_bf16 v[46:49], v[158:161], v[182:185], v[46:49]
	v_mfma_f32_16x16x32_bf16 v[38:41], v[166:169], v[182:185], v[38:41]
	v_mfma_f32_16x16x32_bf16 v[30:33], v[158:161], v[190:193], v[30:33]
	v_mfma_f32_16x16x32_bf16 v[22:25], v[166:169], v[190:193], v[22:25]
	v_mfma_f32_16x16x32_bf16 v[14:17], v[158:161], v[198:201], v[14:17]
	v_mfma_f32_16x16x32_bf16 v[2:5], v[166:169], v[198:201], v[2:5]
	v_mfma_f32_16x16x32_bf16 v[62:65], v[162:165], v[178:181], v[62:65]
	v_mfma_f32_16x16x32_bf16 v[54:57], v[170:173], v[178:181], v[54:57]
	v_mfma_f32_16x16x32_bf16 v[46:49], v[162:165], v[186:189], v[46:49]
	v_mfma_f32_16x16x32_bf16 v[38:41], v[170:173], v[186:189], v[38:41]
	v_mfma_f32_16x16x32_bf16 v[30:33], v[162:165], v[194:197], v[30:33]
	v_mfma_f32_16x16x32_bf16 v[22:25], v[170:173], v[194:197], v[22:25]
	v_mfma_f32_16x16x32_bf16 v[14:17], v[162:165], v[202:205], v[14:17]
	v_mfma_f32_16x16x32_bf16 v[2:5], v[170:173], v[202:205], v[2:5]
	s_barrier
	v_add_u32_e32 v134, 0x18000, v139
	ds_read_b128 v[142:145], v134
	ds_read_b128 v[146:149], v134 offset:1024
	ds_read_b128 v[150:153], v134 offset:2048
	ds_read_b128 v[154:157], v134 offset:3072
	v_add_u32_e32 v134, 0x1c000, v139
	ds_read_b128 v[158:161], v134
	ds_read_b128 v[162:165], v134 offset:1024
	ds_read_b128 v[166:169], v134 offset:2048
	ds_read_b128 v[170:173], v134 offset:3072
	ds_read_b128 v[174:177], v140 offset:32768
	ds_read_b128 v[178:181], v140 offset:33792
	ds_read_b128 v[182:185], v140 offset:34816
	ds_read_b128 v[186:189], v140 offset:35840
	ds_read_b128 v[190:193], v140 offset:36864
	ds_read_b128 v[194:197], v140 offset:37888
	ds_read_b128 v[198:201], v140 offset:38912
	ds_read_b128 v[202:205], v140 offset:39936
	s_add_u32 s2, s34, 0x40000
	s_addc_u32 s3, s35, 0
	s_mov_b32 m0, s59
	s_nop 0
	global_load_lds_dwordx4 v1, s[2:3]
	s_add_u32 s2, s34, 0x60000
	s_addc_u32 s3, s35, 0
	s_mov_b32 m0, s60
	s_nop 0
	global_load_lds_dwordx4 v1, s[2:3]
	s_waitcnt vmcnt(8)
	s_waitcnt lgkmcnt(0)
	s_barrier
	s_waitcnt lgkmcnt(7)
	v_mfma_f32_16x16x32_bf16 v[122:125], v[142:145], v[174:177], v[122:125]
	v_mfma_f32_16x16x32_bf16 v[114:117], v[150:153], v[174:177], v[114:117]
	s_waitcnt lgkmcnt(5)
	v_mfma_f32_16x16x32_bf16 v[106:109], v[142:145], v[182:185], v[106:109]
	v_mfma_f32_16x16x32_bf16 v[98:101], v[150:153], v[182:185], v[98:101]
	s_waitcnt lgkmcnt(3)
	v_mfma_f32_16x16x32_bf16 v[90:93], v[142:145], v[190:193], v[90:93]
	v_mfma_f32_16x16x32_bf16 v[82:85], v[150:153], v[190:193], v[82:85]
	s_waitcnt lgkmcnt(1)
	v_mfma_f32_16x16x32_bf16 v[74:77], v[142:145], v[198:201], v[74:77]
	v_mfma_f32_16x16x32_bf16 v[66:69], v[150:153], v[198:201], v[66:69]
	v_mfma_f32_16x16x32_bf16 v[122:125], v[146:149], v[178:181], v[122:125]
	v_mfma_f32_16x16x32_bf16 v[114:117], v[154:157], v[178:181], v[114:117]
	v_mfma_f32_16x16x32_bf16 v[106:109], v[146:149], v[186:189], v[106:109]
	v_mfma_f32_16x16x32_bf16 v[98:101], v[154:157], v[186:189], v[98:101]
	v_mfma_f32_16x16x32_bf16 v[90:93], v[146:149], v[194:197], v[90:93]
	v_mfma_f32_16x16x32_bf16 v[82:85], v[154:157], v[194:197], v[82:85]
	s_waitcnt lgkmcnt(0)
	v_mfma_f32_16x16x32_bf16 v[74:77], v[146:149], v[202:205], v[74:77]
	v_mfma_f32_16x16x32_bf16 v[66:69], v[154:157], v[202:205], v[66:69]
	v_mfma_f32_16x16x32_bf16 v[126:129], v[158:161], v[174:177], v[126:129]
	v_mfma_f32_16x16x32_bf16 v[118:121], v[166:169], v[174:177], v[118:121]
	v_mfma_f32_16x16x32_bf16 v[110:113], v[158:161], v[182:185], v[110:113]
	v_mfma_f32_16x16x32_bf16 v[102:105], v[166:169], v[182:185], v[102:105]
	v_mfma_f32_16x16x32_bf16 v[94:97], v[158:161], v[190:193], v[94:97]
	v_mfma_f32_16x16x32_bf16 v[86:89], v[166:169], v[190:193], v[86:89]
	v_mfma_f32_16x16x32_bf16 v[78:81], v[158:161], v[198:201], v[78:81]
	v_mfma_f32_16x16x32_bf16 v[70:73], v[166:169], v[198:201], v[70:73]
	v_mfma_f32_16x16x32_bf16 v[126:129], v[162:165], v[178:181], v[126:129]
	v_mfma_f32_16x16x32_bf16 v[118:121], v[170:173], v[178:181], v[118:121]
	v_mfma_f32_16x16x32_bf16 v[110:113], v[162:165], v[186:189], v[110:113]
	v_mfma_f32_16x16x32_bf16 v[102:105], v[170:173], v[186:189], v[102:105]
	v_mfma_f32_16x16x32_bf16 v[94:97], v[162:165], v[194:197], v[94:97]
	v_mfma_f32_16x16x32_bf16 v[86:89], v[170:173], v[194:197], v[86:89]
	v_mfma_f32_16x16x32_bf16 v[78:81], v[162:165], v[202:205], v[78:81]
	v_mfma_f32_16x16x32_bf16 v[70:73], v[170:173], v[202:205], v[70:73]
	s_barrier
	s_add_u32 s2, s50, 0x80
	s_addc_u32 s3, s51, 0
	ds_read_b128 v[174:177], v140 offset:49152
	ds_read_b128 v[178:181], v140 offset:50176
	ds_read_b128 v[182:185], v140 offset:51200
	ds_read_b128 v[186:189], v140 offset:52224
	ds_read_b128 v[190:193], v140 offset:53248
	ds_read_b128 v[194:197], v140 offset:54272
	ds_read_b128 v[198:201], v140 offset:55296
	ds_read_b128 v[202:205], v140 offset:56320
	s_mov_b32 m0, s61
	s_nop 0
	global_load_lds_dwordx4 v136, s[2:3]
	s_add_u32 s2, s50, 0x20080
	s_addc_u32 s3, s51, 0
	s_mov_b32 m0, s62
	s_nop 0
	global_load_lds_dwordx4 v136, s[2:3]
	s_add_u32 s2, s50, 0x40080
	s_addc_u32 s3, s51, 0
	s_mov_b32 m0, s65
	s_nop 0
	global_load_lds_dwordx4 v136, s[2:3]
	s_add_u32 s2, s50, 0x60080
	s_addc_u32 s3, s51, 0
	s_mov_b32 m0, s66
	s_nop 0
	global_load_lds_dwordx4 v136, s[2:3]
	s_mov_b32 m0, s63
	s_nop 0
	global_load_lds_dwordx4 v1, s[44:45]
	s_add_u32 s2, s34, 0x20080
	s_addc_u32 s3, s35, 0
	s_mov_b32 m0, s64
	s_nop 0
	global_load_lds_dwordx4 v1, s[2:3]
	s_waitcnt vmcnt(8)
	s_waitcnt lgkmcnt(0)
	s_barrier
	s_waitcnt lgkmcnt(7)
	v_mfma_f32_16x16x32_bf16 v[58:61], v[142:145], v[174:177], v[58:61]
	v_mfma_f32_16x16x32_bf16 v[50:53], v[150:153], v[174:177], v[50:53]
	s_waitcnt lgkmcnt(5)
	v_mfma_f32_16x16x32_bf16 v[42:45], v[142:145], v[182:185], v[42:45]
	v_mfma_f32_16x16x32_bf16 v[34:37], v[150:153], v[182:185], v[34:37]
	s_waitcnt lgkmcnt(3)
	v_mfma_f32_16x16x32_bf16 v[26:29], v[142:145], v[190:193], v[26:29]
	v_mfma_f32_16x16x32_bf16 v[18:21], v[150:153], v[190:193], v[18:21]
	s_waitcnt lgkmcnt(1)
	v_mfma_f32_16x16x32_bf16 v[10:13], v[142:145], v[198:201], v[10:13]
	v_mfma_f32_16x16x32_bf16 v[6:9], v[150:153], v[198:201], v[6:9]
	v_mfma_f32_16x16x32_bf16 v[58:61], v[146:149], v[178:181], v[58:61]
	v_mfma_f32_16x16x32_bf16 v[50:53], v[154:157], v[178:181], v[50:53]
	v_mfma_f32_16x16x32_bf16 v[42:45], v[146:149], v[186:189], v[42:45]
	v_mfma_f32_16x16x32_bf16 v[34:37], v[154:157], v[186:189], v[34:37]
	v_mfma_f32_16x16x32_bf16 v[26:29], v[146:149], v[194:197], v[26:29]
	v_mfma_f32_16x16x32_bf16 v[18:21], v[154:157], v[194:197], v[18:21]
	s_waitcnt lgkmcnt(0)
	v_mfma_f32_16x16x32_bf16 v[10:13], v[146:149], v[202:205], v[10:13]
	v_mfma_f32_16x16x32_bf16 v[6:9], v[154:157], v[202:205], v[6:9]
	v_mfma_f32_16x16x32_bf16 v[62:65], v[158:161], v[174:177], v[62:65]
	v_mfma_f32_16x16x32_bf16 v[54:57], v[166:169], v[174:177], v[54:57]
	v_mfma_f32_16x16x32_bf16 v[46:49], v[158:161], v[182:185], v[46:49]
	v_mfma_f32_16x16x32_bf16 v[38:41], v[166:169], v[182:185], v[38:41]
	v_mfma_f32_16x16x32_bf16 v[30:33], v[158:161], v[190:193], v[30:33]
	v_mfma_f32_16x16x32_bf16 v[22:25], v[166:169], v[190:193], v[22:25]
	v_mfma_f32_16x16x32_bf16 v[14:17], v[158:161], v[198:201], v[14:17]
	v_mfma_f32_16x16x32_bf16 v[2:5], v[166:169], v[198:201], v[2:5]
	v_mfma_f32_16x16x32_bf16 v[62:65], v[162:165], v[178:181], v[62:65]
	v_mfma_f32_16x16x32_bf16 v[54:57], v[170:173], v[178:181], v[54:57]
	v_mfma_f32_16x16x32_bf16 v[46:49], v[162:165], v[186:189], v[46:49]
	v_mfma_f32_16x16x32_bf16 v[38:41], v[170:173], v[186:189], v[38:41]
	v_mfma_f32_16x16x32_bf16 v[30:33], v[162:165], v[194:197], v[30:33]
	v_mfma_f32_16x16x32_bf16 v[22:25], v[170:173], v[194:197], v[22:25]
	v_mfma_f32_16x16x32_bf16 v[14:17], v[162:165], v[202:205], v[14:17]
	v_mfma_f32_16x16x32_bf16 v[2:5], v[170:173], v[202:205], v[2:5]
	s_barrier
	s_add_i32 s88, s88, 2
	s_add_u32 s86, s86, 0x100
	s_addc_u32 s87, s87, 0
	s_cmp_gt_u32 s88, 13
	s_mov_b64 s[42:43], s[0:1]
	s_cbranch_scc0 .LBB0_800
	s_and_b64 vcc, exec, s[8:9]
	s_cbranch_vccz .LBB0_803
	s_barrier

.LBB0_988:
	v_add_u32_e32 v130, 0x10000, v150
	ds_read_b128 v[152:155], v130
	ds_read_b128 v[156:159], v130 offset:1024
	ds_read_b128 v[160:163], v130 offset:2048
	ds_read_b128 v[164:167], v130 offset:3072
	v_add_u32_e32 v130, 0x14000, v150
	ds_read_b128 v[168:171], v130
	ds_read_b128 v[172:175], v130 offset:1024
	ds_read_b128 v[176:179], v130 offset:2048
	ds_read_b128 v[180:183], v130 offset:3072
	s_add_u32 s0, s40, 0x100
	s_addc_u32 s1, s41, 0
	s_cmp_eq_u32 s88, 12
	s_cselect_b32 s34, s15, s0
	s_cselect_b32 s35, s14, s1
	s_cselect_b32 s44, s25, s86
	s_cselect_b32 s45, s11, s87
	s_add_u32 s42, s34, 0x80
	s_addc_u32 s43, s35, 0
	ds_read_b128 v[184:187], v151
	ds_read_b128 v[188:191], v151 offset:1024
	ds_read_b128 v[192:195], v151 offset:2048
	ds_read_b128 v[196:199], v151 offset:3072
	ds_read_b128 v[200:203], v151 offset:4096
	ds_read_b128 v[204:207], v151 offset:5120
	ds_read_b128 v[208:211], v151 offset:6144
	ds_read_b128 v[212:215], v151 offset:7168
	s_add_u32 s12, s40, 0x40080
	s_addc_u32 s13, s41, 0
	s_mov_b32 m0, s82
	s_nop 0
	global_load_lds_dwordx4 v1, s[12:13]
	s_add_u32 s12, s40, 0x60080
	s_addc_u32 s13, s41, 0
	s_add_i32 s40, s54, 0xe000
	s_mov_b32 m0, s40
	s_nop 0
	global_load_lds_dwordx4 v1, s[12:13]
	s_waitcnt vmcnt(8)
	s_waitcnt lgkmcnt(0)
	s_barrier
	s_waitcnt lgkmcnt(7)
	v_mfma_f32_16x16x32_bf16 v[122:125], v[152:155], v[184:187], v[122:125]
	v_mfma_f32_16x16x32_bf16 v[114:117], v[160:163], v[184:187], v[114:117]
	s_waitcnt lgkmcnt(5)
	v_mfma_f32_16x16x32_bf16 v[106:109], v[152:155], v[192:195], v[106:109]
	v_mfma_f32_16x16x32_bf16 v[98:101], v[160:163], v[192:195], v[98:101]
	s_waitcnt lgkmcnt(3)
	v_mfma_f32_16x16x32_bf16 v[90:93], v[152:155], v[200:203], v[90:93]
	v_mfma_f32_16x16x32_bf16 v[82:85], v[160:163], v[200:203], v[82:85]
	s_waitcnt lgkmcnt(1)
	v_mfma_f32_16x16x32_bf16 v[74:77], v[152:155], v[208:211], v[74:77]
	v_mfma_f32_16x16x32_bf16 v[66:69], v[160:163], v[208:211], v[66:69]
	v_mfma_f32_16x16x32_bf16 v[122:125], v[156:159], v[188:191], v[122:125]
	v_mfma_f32_16x16x32_bf16 v[114:117], v[164:167], v[188:191], v[114:117]
	v_mfma_f32_16x16x32_bf16 v[106:109], v[156:159], v[196:199], v[106:109]
	v_mfma_f32_16x16x32_bf16 v[98:101], v[164:167], v[196:199], v[98:101]
	v_mfma_f32_16x16x32_bf16 v[90:93], v[156:159], v[204:207], v[90:93]
	v_mfma_f32_16x16x32_bf16 v[82:85], v[164:167], v[204:207], v[82:85]
	s_waitcnt lgkmcnt(0)
	v_mfma_f32_16x16x32_bf16 v[74:77], v[156:159], v[212:215], v[74:77]
	v_mfma_f32_16x16x32_bf16 v[66:69], v[164:167], v[212:215], v[66:69]
	v_mfma_f32_16x16x32_bf16 v[126:129], v[168:171], v[184:187], v[126:129]
	v_mfma_f32_16x16x32_bf16 v[118:121], v[176:179], v[184:187], v[118:121]
	v_mfma_f32_16x16x32_bf16 v[110:113], v[168:171], v[192:195], v[110:113]
	v_mfma_f32_16x16x32_bf16 v[102:105], v[176:179], v[192:195], v[102:105]
	v_mfma_f32_16x16x32_bf16 v[94:97], v[168:171], v[200:203], v[94:97]
	v_mfma_f32_16x16x32_bf16 v[86:89], v[176:179], v[200:203], v[86:89]
	v_mfma_f32_16x16x32_bf16 v[78:81], v[168:171], v[208:211], v[78:81]
	v_mfma_f32_16x16x32_bf16 v[70:73], v[176:179], v[208:211], v[70:73]
	v_mfma_f32_16x16x32_bf16 v[126:129], v[172:175], v[188:191], v[126:129]
	v_mfma_f32_16x16x32_bf16 v[118:121], v[180:183], v[188:191], v[118:121]
	v_mfma_f32_16x16x32_bf16 v[110:113], v[172:175], v[196:199], v[110:113]
	v_mfma_f32_16x16x32_bf16 v[102:105], v[180:183], v[196:199], v[102:105]
	v_mfma_f32_16x16x32_bf16 v[94:97], v[172:175], v[204:207], v[94:97]
	v_mfma_f32_16x16x32_bf16 v[86:89], v[180:183], v[204:207], v[86:89]
	v_mfma_f32_16x16x32_bf16 v[78:81], v[172:175], v[212:215], v[78:81]
	v_mfma_f32_16x16x32_bf16 v[70:73], v[180:183], v[212:215], v[70:73]
	s_barrier
	ds_read_b128 v[184:187], v151 offset:16384
	ds_read_b128 v[188:191], v151 offset:17408
	ds_read_b128 v[192:195], v151 offset:18432
	ds_read_b128 v[196:199], v151 offset:19456
	ds_read_b128 v[200:203], v151 offset:20480
	ds_read_b128 v[204:207], v151 offset:21504
	ds_read_b128 v[208:211], v151 offset:22528
	ds_read_b128 v[212:215], v151 offset:23552
	s_mov_b32 m0, s56
	s_nop 0
	global_load_lds_dwordx4 v144, s[44:45]
	s_add_u32 s12, s44, 0x20000
	s_addc_u32 s13, s45, 0
	s_mov_b32 m0, s57
	s_nop 0
	global_load_lds_dwordx4 v144, s[12:13]
	s_add_u32 s12, s44, 0x40000
	s_addc_u32 s13, s45, 0
	s_mov_b32 m0, s58
	s_nop 0
	global_load_lds_dwordx4 v144, s[12:13]
	s_add_u32 s12, s44, 0x60000
	s_addc_u32 s13, s45, 0
	s_mov_b32 m0, s59
	s_nop 0
	global_load_lds_dwordx4 v144, s[12:13]
	s_mov_b32 m0, s54
	s_nop 0
	global_load_lds_dwordx4 v1, s[34:35]
	s_add_u32 s12, s34, 0x20000
	s_addc_u32 s13, s35, 0
	s_mov_b32 m0, s60
	s_nop 0
	global_load_lds_dwordx4 v1, s[12:13]
	s_waitcnt vmcnt(8)
	s_waitcnt lgkmcnt(0)
	s_barrier
	s_waitcnt lgkmcnt(7)
	v_mfma_f32_16x16x32_bf16 v[58:61], v[152:155], v[184:187], v[58:61]
	v_mfma_f32_16x16x32_bf16 v[50:53], v[160:163], v[184:187], v[50:53]
	s_waitcnt lgkmcnt(5)
	v_mfma_f32_16x16x32_bf16 v[42:45], v[152:155], v[192:195], v[42:45]
	v_mfma_f32_16x16x32_bf16 v[34:37], v[160:163], v[192:195], v[34:37]
	s_waitcnt lgkmcnt(3)
	v_mfma_f32_16x16x32_bf16 v[26:29], v[152:155], v[200:203], v[26:29]
	v_mfma_f32_16x16x32_bf16 v[18:21], v[160:163], v[200:203], v[18:21]
	s_waitcnt lgkmcnt(1)
	v_mfma_f32_16x16x32_bf16 v[10:13], v[152:155], v[208:211], v[10:13]
	v_mfma_f32_16x16x32_bf16 v[6:9], v[160:163], v[208:211], v[6:9]
	v_mfma_f32_16x16x32_bf16 v[58:61], v[156:159], v[188:191], v[58:61]
	v_mfma_f32_16x16x32_bf16 v[50:53], v[164:167], v[188:191], v[50:53]
	v_mfma_f32_16x16x32_bf16 v[42:45], v[156:159], v[196:199], v[42:45]
	v_mfma_f32_16x16x32_bf16 v[34:37], v[164:167], v[196:199], v[34:37]
	v_mfma_f32_16x16x32_bf16 v[26:29], v[156:159], v[204:207], v[26:29]
	v_mfma_f32_16x16x32_bf16 v[18:21], v[164:167], v[204:207], v[18:21]
	s_waitcnt lgkmcnt(0)
	v_mfma_f32_16x16x32_bf16 v[10:13], v[156:159], v[212:215], v[10:13]
	v_mfma_f32_16x16x32_bf16 v[6:9], v[164:167], v[212:215], v[6:9]
	v_mfma_f32_16x16x32_bf16 v[62:65], v[168:171], v[184:187], v[62:65]
	v_mfma_f32_16x16x32_bf16 v[54:57], v[176:179], v[184:187], v[54:57]
	v_mfma_f32_16x16x32_bf16 v[46:49], v[168:171], v[192:195], v[46:49]
	v_mfma_f32_16x16x32_bf16 v[38:41], v[176:179], v[192:195], v[38:41]
	v_mfma_f32_16x16x32_bf16 v[30:33], v[168:171], v[200:203], v[30:33]
	v_mfma_f32_16x16x32_bf16 v[22:25], v[176:179], v[200:203], v[22:25]
	v_mfma_f32_16x16x32_bf16 v[14:17], v[168:171], v[208:211], v[14:17]
	v_mfma_f32_16x16x32_bf16 v[2:5], v[176:179], v[208:211], v[2:5]
	v_mfma_f32_16x16x32_bf16 v[62:65], v[172:175], v[188:191], v[62:65]
	v_mfma_f32_16x16x32_bf16 v[54:57], v[180:183], v[188:191], v[54:57]
	v_mfma_f32_16x16x32_bf16 v[46:49], v[172:175], v[196:199], v[46:49]
	v_mfma_f32_16x16x32_bf16 v[38:41], v[180:183], v[196:199], v[38:41]
	v_mfma_f32_16x16x32_bf16 v[30:33], v[172:175], v[204:207], v[30:33]
	v_mfma_f32_16x16x32_bf16 v[22:25], v[180:183], v[204:207], v[22:25]
	v_mfma_f32_16x16x32_bf16 v[14:17], v[172:175], v[212:215], v[14:17]
	v_mfma_f32_16x16x32_bf16 v[2:5], v[180:183], v[212:215], v[2:5]
	s_barrier
	v_add_u32_e32 v130, 0x18000, v150
	ds_read_b128 v[152:155], v130
	ds_read_b128 v[156:159], v130 offset:1024
	ds_read_b128 v[160:163], v130 offset:2048
	ds_read_b128 v[164:167], v130 offset:3072
	v_add_u32_e32 v130, 0x1c000, v150
	ds_read_b128 v[168:171], v130
	ds_read_b128 v[172:175], v130 offset:1024
	ds_read_b128 v[176:179], v130 offset:2048
	ds_read_b128 v[180:183], v130 offset:3072
	ds_read_b128 v[184:187], v151 offset:32768
	ds_read_b128 v[188:191], v151 offset:33792
	ds_read_b128 v[192:195], v151 offset:34816
	ds_read_b128 v[196:199], v151 offset:35840
	ds_read_b128 v[200:203], v151 offset:36864
	ds_read_b128 v[204:207], v151 offset:37888
	ds_read_b128 v[208:211], v151 offset:38912
	ds_read_b128 v[212:215], v151 offset:39936
	s_add_u32 s12, s34, 0x40000
	s_addc_u32 s13, s35, 0
	s_mov_b32 m0, s61
	s_nop 0
	global_load_lds_dwordx4 v1, s[12:13]
	s_add_u32 s12, s34, 0x60000
	s_addc_u32 s13, s35, 0
	s_mov_b32 m0, s62
	s_nop 0
	global_load_lds_dwordx4 v1, s[12:13]
	s_waitcnt vmcnt(8)
	s_waitcnt lgkmcnt(0)
	s_barrier
	s_waitcnt lgkmcnt(7)
	v_mfma_f32_16x16x32_bf16 v[122:125], v[152:155], v[184:187], v[122:125]
	v_mfma_f32_16x16x32_bf16 v[114:117], v[160:163], v[184:187], v[114:117]
	s_waitcnt lgkmcnt(5)
	v_mfma_f32_16x16x32_bf16 v[106:109], v[152:155], v[192:195], v[106:109]
	v_mfma_f32_16x16x32_bf16 v[98:101], v[160:163], v[192:195], v[98:101]
	s_waitcnt lgkmcnt(3)
	v_mfma_f32_16x16x32_bf16 v[90:93], v[152:155], v[200:203], v[90:93]
	v_mfma_f32_16x16x32_bf16 v[82:85], v[160:163], v[200:203], v[82:85]
	s_waitcnt lgkmcnt(1)
	v_mfma_f32_16x16x32_bf16 v[74:77], v[152:155], v[208:211], v[74:77]
	v_mfma_f32_16x16x32_bf16 v[66:69], v[160:163], v[208:211], v[66:69]
	v_mfma_f32_16x16x32_bf16 v[122:125], v[156:159], v[188:191], v[122:125]
	v_mfma_f32_16x16x32_bf16 v[114:117], v[164:167], v[188:191], v[114:117]
	v_mfma_f32_16x16x32_bf16 v[106:109], v[156:159], v[196:199], v[106:109]
	v_mfma_f32_16x16x32_bf16 v[98:101], v[164:167], v[196:199], v[98:101]
	v_mfma_f32_16x16x32_bf16 v[90:93], v[156:159], v[204:207], v[90:93]
	v_mfma_f32_16x16x32_bf16 v[82:85], v[164:167], v[204:207], v[82:85]
	s_waitcnt lgkmcnt(0)
	v_mfma_f32_16x16x32_bf16 v[74:77], v[156:159], v[212:215], v[74:77]
	v_mfma_f32_16x16x32_bf16 v[66:69], v[164:167], v[212:215], v[66:69]
	v_mfma_f32_16x16x32_bf16 v[126:129], v[168:171], v[184:187], v[126:129]
	v_mfma_f32_16x16x32_bf16 v[118:121], v[176:179], v[184:187], v[118:121]
	v_mfma_f32_16x16x32_bf16 v[110:113], v[168:171], v[192:195], v[110:113]
	v_mfma_f32_16x16x32_bf16 v[102:105], v[176:179], v[192:195], v[102:105]
	v_mfma_f32_16x16x32_bf16 v[94:97], v[168:171], v[200:203], v[94:97]
	v_mfma_f32_16x16x32_bf16 v[86:89], v[176:179], v[200:203], v[86:89]
	v_mfma_f32_16x16x32_bf16 v[78:81], v[168:171], v[208:211], v[78:81]
	v_mfma_f32_16x16x32_bf16 v[70:73], v[176:179], v[208:211], v[70:73]
	v_mfma_f32_16x16x32_bf16 v[126:129], v[172:175], v[188:191], v[126:129]
	v_mfma_f32_16x16x32_bf16 v[118:121], v[180:183], v[188:191], v[118:121]
	v_mfma_f32_16x16x32_bf16 v[110:113], v[172:175], v[196:199], v[110:113]
	v_mfma_f32_16x16x32_bf16 v[102:105], v[180:183], v[196:199], v[102:105]
	v_mfma_f32_16x16x32_bf16 v[94:97], v[172:175], v[204:207], v[94:97]
	v_mfma_f32_16x16x32_bf16 v[86:89], v[180:183], v[204:207], v[86:89]
	v_mfma_f32_16x16x32_bf16 v[78:81], v[172:175], v[212:215], v[78:81]
	v_mfma_f32_16x16x32_bf16 v[70:73], v[180:183], v[212:215], v[70:73]
	s_barrier
	s_add_u32 s12, s44, 0x80
	s_addc_u32 s13, s45, 0
	ds_read_b128 v[184:187], v151 offset:49152
	ds_read_b128 v[188:191], v151 offset:50176
	ds_read_b128 v[192:195], v151 offset:51200
	ds_read_b128 v[196:199], v151 offset:52224
	ds_read_b128 v[200:203], v151 offset:53248
	ds_read_b128 v[204:207], v151 offset:54272
	ds_read_b128 v[208:211], v151 offset:55296
	ds_read_b128 v[212:215], v151 offset:56320
	s_mov_b32 m0, s63
	s_nop 0
	global_load_lds_dwordx4 v144, s[12:13]
	s_add_u32 s12, s44, 0x20080
	s_addc_u32 s13, s45, 0
	s_mov_b32 m0, s64
	s_nop 0
	global_load_lds_dwordx4 v144, s[12:13]
	s_add_u32 s12, s44, 0x40080
	s_addc_u32 s13, s45, 0
	s_mov_b32 m0, s67
	s_nop 0
	global_load_lds_dwordx4 v144, s[12:13]
	s_add_u32 s12, s44, 0x60080
	s_addc_u32 s13, s45, 0
	s_mov_b32 m0, s73
	s_nop 0
	global_load_lds_dwordx4 v144, s[12:13]
	s_mov_b32 m0, s65
	s_nop 0
	global_load_lds_dwordx4 v1, s[42:43]
	s_add_u32 s12, s34, 0x20080
	s_addc_u32 s13, s35, 0
	s_mov_b32 m0, s66
	s_nop 0
	global_load_lds_dwordx4 v1, s[12:13]
	s_waitcnt vmcnt(8)
	s_waitcnt lgkmcnt(0)
	s_barrier
	s_waitcnt lgkmcnt(7)
	v_mfma_f32_16x16x32_bf16 v[58:61], v[152:155], v[184:187], v[58:61]
	v_mfma_f32_16x16x32_bf16 v[50:53], v[160:163], v[184:187], v[50:53]
	s_waitcnt lgkmcnt(5)
	v_mfma_f32_16x16x32_bf16 v[42:45], v[152:155], v[192:195], v[42:45]
	v_mfma_f32_16x16x32_bf16 v[34:37], v[160:163], v[192:195], v[34:37]
	s_waitcnt lgkmcnt(3)
	v_mfma_f32_16x16x32_bf16 v[26:29], v[152:155], v[200:203], v[26:29]
	v_mfma_f32_16x16x32_bf16 v[18:21], v[160:163], v[200:203], v[18:21]
	s_waitcnt lgkmcnt(1)
	v_mfma_f32_16x16x32_bf16 v[10:13], v[152:155], v[208:211], v[10:13]
	v_mfma_f32_16x16x32_bf16 v[6:9], v[160:163], v[208:211], v[6:9]
	v_mfma_f32_16x16x32_bf16 v[58:61], v[156:159], v[188:191], v[58:61]
	v_mfma_f32_16x16x32_bf16 v[50:53], v[164:167], v[188:191], v[50:53]
	v_mfma_f32_16x16x32_bf16 v[42:45], v[156:159], v[196:199], v[42:45]
	v_mfma_f32_16x16x32_bf16 v[34:37], v[164:167], v[196:199], v[34:37]
	v_mfma_f32_16x16x32_bf16 v[26:29], v[156:159], v[204:207], v[26:29]
	v_mfma_f32_16x16x32_bf16 v[18:21], v[164:167], v[204:207], v[18:21]
	s_waitcnt lgkmcnt(0)
	v_mfma_f32_16x16x32_bf16 v[10:13], v[156:159], v[212:215], v[10:13]
	v_mfma_f32_16x16x32_bf16 v[6:9], v[164:167], v[212:215], v[6:9]
	v_mfma_f32_16x16x32_bf16 v[62:65], v[168:171], v[184:187], v[62:65]
	v_mfma_f32_16x16x32_bf16 v[54:57], v[176:179], v[184:187], v[54:57]
	v_mfma_f32_16x16x32_bf16 v[46:49], v[168:171], v[192:195], v[46:49]
	v_mfma_f32_16x16x32_bf16 v[38:41], v[176:179], v[192:195], v[38:41]
	v_mfma_f32_16x16x32_bf16 v[30:33], v[168:171], v[200:203], v[30:33]
	v_mfma_f32_16x16x32_bf16 v[22:25], v[176:179], v[200:203], v[22:25]
	v_mfma_f32_16x16x32_bf16 v[14:17], v[168:171], v[208:211], v[14:17]
	v_mfma_f32_16x16x32_bf16 v[2:5], v[176:179], v[208:211], v[2:5]
	v_mfma_f32_16x16x32_bf16 v[62:65], v[172:175], v[188:191], v[62:65]
	v_mfma_f32_16x16x32_bf16 v[54:57], v[180:183], v[188:191], v[54:57]
	v_mfma_f32_16x16x32_bf16 v[46:49], v[172:175], v[196:199], v[46:49]
	v_mfma_f32_16x16x32_bf16 v[38:41], v[180:183], v[196:199], v[38:41]
	v_mfma_f32_16x16x32_bf16 v[30:33], v[172:175], v[204:207], v[30:33]
	v_mfma_f32_16x16x32_bf16 v[22:25], v[180:183], v[204:207], v[22:25]
	v_mfma_f32_16x16x32_bf16 v[14:17], v[172:175], v[212:215], v[14:17]
	v_mfma_f32_16x16x32_bf16 v[2:5], v[180:183], v[212:215], v[2:5]
	s_barrier
	s_add_i32 s88, s88, 2
	s_add_u32 s86, s86, 0x100
	s_addc_u32 s87, s87, 0
	s_cmp_gt_u32 s88, 13
	s_mov_b64 s[40:41], s[0:1]
	s_cbranch_scc0 .LBB0_988
	s_and_b64 vcc, exec, s[8:9]
	s_cbranch_vccz .LBB0_991
	s_barrier

.LBB0_1317:
	ds_read_b128 v[138:141], v132
	ds_read_b128 v[142:145], v132 offset:1024
	ds_read_b128 v[146:149], v132 offset:2048
	ds_read_b128 v[150:153], v132 offset:3072
	ds_read_b128 v[154:157], v133
	ds_read_b128 v[158:161], v133 offset:1024
	ds_read_b128 v[166:169], v133 offset:2048
	ds_read_b128 v[170:173], v133 offset:3072
	s_add_u32 s0, s46, 0xea3c0080
	s_addc_u32 s1, s47, -1
	s_cmp_lg_u32 s90, 12
	s_cselect_b32 s13, s0, 0
	s_cselect_b32 s12, s1, 0
	s_add_u32 s0, s8, s13
	s_addc_u32 s1, s9, s12
	s_add_u32 s34, s0, 0x80
	s_addc_u32 s35, s1, 0
	s_add_u32 s48, s4, s13
	s_addc_u32 s49, s5, s12
	ds_read_b128 v[174:177], v134
	ds_read_b128 v[184:187], v134 offset:1024
	ds_read_b128 v[188:191], v134 offset:2048
	ds_read_b128 v[192:195], v134 offset:3072
	ds_read_b128 v[196:199], v134 offset:4096
	ds_read_b128 v[200:203], v134 offset:5120
	ds_read_b128 v[204:207], v134 offset:6144
	ds_read_b128 v[208:211], v134 offset:7168
	s_add_u32 s12, s88, s46
	s_addc_u32 s13, s89, s47
	s_mov_b32 m0, s87
	s_nop 0
	global_load_lds_dwordx4 v130, s[12:13]
	s_add_u32 s12, s12, 0x20000
	s_addc_u32 s13, s13, 0
	s_add_i32 s91, s66, 0xe000
	s_mov_b32 m0, s91
	s_nop 0
	global_load_lds_dwordx4 v130, s[12:13]
	s_waitcnt vmcnt(8)
	s_waitcnt lgkmcnt(0)
	s_barrier
	s_waitcnt lgkmcnt(7)
	v_mfma_f32_16x16x32_bf16 v[2:5], v[138:141], v[174:177], v[2:5]
	v_mfma_f32_16x16x32_bf16 v[6:9], v[146:149], v[174:177], v[6:9]
	s_waitcnt lgkmcnt(5)
	v_mfma_f32_16x16x32_bf16 v[30:33], v[138:141], v[188:191], v[30:33]
	v_mfma_f32_16x16x32_bf16 v[34:37], v[146:149], v[188:191], v[34:37]
	s_waitcnt lgkmcnt(3)
	v_mfma_f32_16x16x32_bf16 v[54:57], v[138:141], v[196:199], v[54:57]
	v_mfma_f32_16x16x32_bf16 v[50:53], v[146:149], v[196:199], v[50:53]
	s_waitcnt lgkmcnt(1)
	v_mfma_f32_16x16x32_bf16 v[70:73], v[138:141], v[204:207], v[70:73]
	v_mfma_f32_16x16x32_bf16 v[66:69], v[146:149], v[204:207], v[66:69]
	v_mfma_f32_16x16x32_bf16 v[2:5], v[142:145], v[184:187], v[2:5]
	v_mfma_f32_16x16x32_bf16 v[6:9], v[150:153], v[184:187], v[6:9]
	v_mfma_f32_16x16x32_bf16 v[30:33], v[142:145], v[192:195], v[30:33]
	v_mfma_f32_16x16x32_bf16 v[34:37], v[150:153], v[192:195], v[34:37]
	v_mfma_f32_16x16x32_bf16 v[54:57], v[142:145], v[200:203], v[54:57]
	v_mfma_f32_16x16x32_bf16 v[50:53], v[150:153], v[200:203], v[50:53]
	s_waitcnt lgkmcnt(0)
	v_mfma_f32_16x16x32_bf16 v[70:73], v[142:145], v[208:211], v[70:73]
	v_mfma_f32_16x16x32_bf16 v[66:69], v[150:153], v[208:211], v[66:69]
	v_mfma_f32_16x16x32_bf16 v[10:13], v[154:157], v[174:177], v[10:13]
	v_mfma_f32_16x16x32_bf16 v[14:17], v[166:169], v[174:177], v[14:17]
	v_mfma_f32_16x16x32_bf16 v[22:25], v[154:157], v[188:191], v[22:25]
	v_mfma_f32_16x16x32_bf16 v[18:21], v[166:169], v[188:191], v[18:21]
	v_mfma_f32_16x16x32_bf16 v[38:41], v[154:157], v[196:199], v[38:41]
	v_mfma_f32_16x16x32_bf16 v[26:29], v[166:169], v[196:199], v[26:29]
	v_mfma_f32_16x16x32_bf16 v[46:49], v[154:157], v[204:207], v[46:49]
	v_mfma_f32_16x16x32_bf16 v[42:45], v[166:169], v[204:207], v[42:45]
	v_mfma_f32_16x16x32_bf16 v[10:13], v[158:161], v[184:187], v[10:13]
	v_mfma_f32_16x16x32_bf16 v[14:17], v[170:173], v[184:187], v[14:17]
	v_mfma_f32_16x16x32_bf16 v[22:25], v[158:161], v[192:195], v[22:25]
	v_mfma_f32_16x16x32_bf16 v[18:21], v[170:173], v[192:195], v[18:21]
	v_mfma_f32_16x16x32_bf16 v[38:41], v[158:161], v[200:203], v[38:41]
	v_mfma_f32_16x16x32_bf16 v[26:29], v[170:173], v[200:203], v[26:29]
	v_mfma_f32_16x16x32_bf16 v[46:49], v[158:161], v[208:211], v[46:49]
	v_mfma_f32_16x16x32_bf16 v[42:45], v[170:173], v[208:211], v[42:45]
	s_barrier
	ds_read_b128 v[174:177], v134 offset:16384
	ds_read_b128 v[184:187], v134 offset:17408
	ds_read_b128 v[188:191], v134 offset:18432
	ds_read_b128 v[192:195], v134 offset:19456
	ds_read_b128 v[196:199], v134 offset:20480
	ds_read_b128 v[200:203], v134 offset:21504
	ds_read_b128 v[204:207], v134 offset:22528
	ds_read_b128 v[208:211], v134 offset:23552
	s_mov_b32 m0, s67
	s_nop 0
	global_load_lds_dwordx4 v131, s[48:49]
	s_add_u32 s12, s48, 0x20000
	s_addc_u32 s13, s49, 0
	s_mov_b32 m0, s73
	s_nop 0
	global_load_lds_dwordx4 v131, s[12:13]
	s_add_u32 s12, s48, 0x40000
	s_addc_u32 s13, s49, 0
	s_mov_b32 m0, s74
	s_nop 0
	global_load_lds_dwordx4 v131, s[12:13]
	s_add_u32 s12, s48, 0x60000
	s_addc_u32 s13, s49, 0
	s_mov_b32 m0, s75
	s_nop 0
	global_load_lds_dwordx4 v131, s[12:13]
	s_mov_b32 m0, s66
	s_nop 0
	global_load_lds_dwordx4 v130, s[0:1]
	s_add_u32 s12, s0, 0x20000
	s_addc_u32 s13, s1, 0
	s_mov_b32 m0, s76
	s_nop 0
	global_load_lds_dwordx4 v130, s[12:13]
	s_waitcnt vmcnt(8)
	s_waitcnt lgkmcnt(0)
	s_barrier
	s_waitcnt lgkmcnt(7)
	v_mfma_f32_16x16x32_bf16 v[82:85], v[138:141], v[174:177], v[82:85]
	v_mfma_f32_16x16x32_bf16 v[74:77], v[146:149], v[174:177], v[74:77]
	s_waitcnt lgkmcnt(5)
	v_mfma_f32_16x16x32_bf16 v[98:101], v[138:141], v[188:191], v[98:101]
	v_mfma_f32_16x16x32_bf16 v[90:93], v[146:149], v[188:191], v[90:93]
	s_waitcnt lgkmcnt(3)
	v_mfma_f32_16x16x32_bf16 v[118:121], v[138:141], v[196:199], v[118:121]
	v_mfma_f32_16x16x32_bf16 v[114:117], v[146:149], v[196:199], v[114:117]
	s_waitcnt lgkmcnt(1)
	v_mfma_f32_16x16x32_bf16 v[126:129], v[138:141], v[204:207], v[126:129]
	v_mfma_f32_16x16x32_bf16 v[122:125], v[146:149], v[204:207], v[122:125]
	v_mfma_f32_16x16x32_bf16 v[82:85], v[142:145], v[184:187], v[82:85]
	v_mfma_f32_16x16x32_bf16 v[74:77], v[150:153], v[184:187], v[74:77]
	v_mfma_f32_16x16x32_bf16 v[98:101], v[142:145], v[192:195], v[98:101]
	v_mfma_f32_16x16x32_bf16 v[90:93], v[150:153], v[192:195], v[90:93]
	v_mfma_f32_16x16x32_bf16 v[118:121], v[142:145], v[200:203], v[118:121]
	v_mfma_f32_16x16x32_bf16 v[114:117], v[150:153], v[200:203], v[114:117]
	s_waitcnt lgkmcnt(0)
	v_mfma_f32_16x16x32_bf16 v[126:129], v[142:145], v[208:211], v[126:129]
	v_mfma_f32_16x16x32_bf16 v[122:125], v[150:153], v[208:211], v[122:125]
	v_mfma_f32_16x16x32_bf16 v[62:65], v[154:157], v[174:177], v[62:65]
	v_mfma_f32_16x16x32_bf16 v[58:61], v[166:169], v[174:177], v[58:61]
	v_mfma_f32_16x16x32_bf16 v[86:89], v[154:157], v[188:191], v[86:89]
	v_mfma_f32_16x16x32_bf16 v[78:81], v[166:169], v[188:191], v[78:81]
	v_mfma_f32_16x16x32_bf16 v[102:105], v[154:157], v[196:199], v[102:105]
	v_mfma_f32_16x16x32_bf16 v[94:97], v[166:169], v[196:199], v[94:97]
	v_mfma_f32_16x16x32_bf16 v[110:113], v[154:157], v[204:207], v[110:113]
	v_mfma_f32_16x16x32_bf16 v[106:109], v[166:169], v[204:207], v[106:109]
	v_mfma_f32_16x16x32_bf16 v[62:65], v[158:161], v[184:187], v[62:65]
	v_mfma_f32_16x16x32_bf16 v[58:61], v[170:173], v[184:187], v[58:61]
	v_mfma_f32_16x16x32_bf16 v[86:89], v[158:161], v[192:195], v[86:89]
	v_mfma_f32_16x16x32_bf16 v[78:81], v[170:173], v[192:195], v[78:81]
	v_mfma_f32_16x16x32_bf16 v[102:105], v[158:161], v[200:203], v[102:105]
	v_mfma_f32_16x16x32_bf16 v[94:97], v[170:173], v[200:203], v[94:97]
	v_mfma_f32_16x16x32_bf16 v[110:113], v[158:161], v[208:211], v[110:113]
	v_mfma_f32_16x16x32_bf16 v[106:109], v[170:173], v[208:211], v[106:109]
	s_barrier
	ds_read_b128 v[138:141], v135
	ds_read_b128 v[142:145], v135 offset:1024
	ds_read_b128 v[146:149], v135 offset:2048
	ds_read_b128 v[150:153], v135 offset:3072
	ds_read_b128 v[154:157], v136
	ds_read_b128 v[158:161], v136 offset:1024
	ds_read_b128 v[166:169], v136 offset:2048
	ds_read_b128 v[170:173], v136 offset:3072
	ds_read_b128 v[174:177], v134 offset:32768
	ds_read_b128 v[184:187], v134 offset:33792
	ds_read_b128 v[188:191], v134 offset:34816
	ds_read_b128 v[192:195], v134 offset:35840
	ds_read_b128 v[196:199], v134 offset:36864
	ds_read_b128 v[200:203], v134 offset:37888
	ds_read_b128 v[204:207], v134 offset:38912
	ds_read_b128 v[208:211], v134 offset:39936
	s_add_u32 s12, s0, 0x40000
	s_addc_u32 s13, s1, 0
	s_mov_b32 m0, s77
	s_nop 0
	global_load_lds_dwordx4 v130, s[12:13]
	s_add_u32 s12, s0, 0x60000
	s_addc_u32 s13, s1, 0
	s_mov_b32 m0, s79
	s_nop 0
	global_load_lds_dwordx4 v130, s[12:13]
	s_waitcnt vmcnt(8)
	s_waitcnt lgkmcnt(0)
	s_barrier
	s_waitcnt lgkmcnt(7)
	v_mfma_f32_16x16x32_bf16 v[2:5], v[138:141], v[174:177], v[2:5]
	v_mfma_f32_16x16x32_bf16 v[6:9], v[146:149], v[174:177], v[6:9]
	s_waitcnt lgkmcnt(5)
	v_mfma_f32_16x16x32_bf16 v[30:33], v[138:141], v[188:191], v[30:33]
	v_mfma_f32_16x16x32_bf16 v[34:37], v[146:149], v[188:191], v[34:37]
	s_waitcnt lgkmcnt(3)
	v_mfma_f32_16x16x32_bf16 v[54:57], v[138:141], v[196:199], v[54:57]
	v_mfma_f32_16x16x32_bf16 v[50:53], v[146:149], v[196:199], v[50:53]
	s_waitcnt lgkmcnt(1)
	v_mfma_f32_16x16x32_bf16 v[70:73], v[138:141], v[204:207], v[70:73]
	v_mfma_f32_16x16x32_bf16 v[66:69], v[146:149], v[204:207], v[66:69]
	v_mfma_f32_16x16x32_bf16 v[2:5], v[142:145], v[184:187], v[2:5]
	v_mfma_f32_16x16x32_bf16 v[6:9], v[150:153], v[184:187], v[6:9]
	v_mfma_f32_16x16x32_bf16 v[30:33], v[142:145], v[192:195], v[30:33]
	v_mfma_f32_16x16x32_bf16 v[34:37], v[150:153], v[192:195], v[34:37]
	v_mfma_f32_16x16x32_bf16 v[54:57], v[142:145], v[200:203], v[54:57]
	v_mfma_f32_16x16x32_bf16 v[50:53], v[150:153], v[200:203], v[50:53]
	s_waitcnt lgkmcnt(0)
	v_mfma_f32_16x16x32_bf16 v[70:73], v[142:145], v[208:211], v[70:73]
	v_mfma_f32_16x16x32_bf16 v[66:69], v[150:153], v[208:211], v[66:69]
	v_mfma_f32_16x16x32_bf16 v[10:13], v[154:157], v[174:177], v[10:13]
	v_mfma_f32_16x16x32_bf16 v[14:17], v[166:169], v[174:177], v[14:17]
	v_mfma_f32_16x16x32_bf16 v[22:25], v[154:157], v[188:191], v[22:25]
	v_mfma_f32_16x16x32_bf16 v[18:21], v[166:169], v[188:191], v[18:21]
	v_mfma_f32_16x16x32_bf16 v[38:41], v[154:157], v[196:199], v[38:41]
	v_mfma_f32_16x16x32_bf16 v[26:29], v[166:169], v[196:199], v[26:29]
	v_mfma_f32_16x16x32_bf16 v[46:49], v[154:157], v[204:207], v[46:49]
	v_mfma_f32_16x16x32_bf16 v[42:45], v[166:169], v[204:207], v[42:45]
	v_mfma_f32_16x16x32_bf16 v[10:13], v[158:161], v[184:187], v[10:13]
	v_mfma_f32_16x16x32_bf16 v[14:17], v[170:173], v[184:187], v[14:17]
	v_mfma_f32_16x16x32_bf16 v[22:25], v[158:161], v[192:195], v[22:25]
	v_mfma_f32_16x16x32_bf16 v[18:21], v[170:173], v[192:195], v[18:21]
	v_mfma_f32_16x16x32_bf16 v[38:41], v[158:161], v[200:203], v[38:41]
	v_mfma_f32_16x16x32_bf16 v[26:29], v[170:173], v[200:203], v[26:29]
	v_mfma_f32_16x16x32_bf16 v[46:49], v[158:161], v[208:211], v[46:49]
	v_mfma_f32_16x16x32_bf16 v[42:45], v[170:173], v[208:211], v[42:45]
	s_barrier
	s_add_u32 s12, s48, 0x80
	s_addc_u32 s13, s49, 0
	ds_read_b128 v[174:177], v134 offset:49152
	ds_read_b128 v[184:187], v134 offset:50176
	ds_read_b128 v[188:191], v134 offset:51200
	ds_read_b128 v[192:195], v134 offset:52224
	ds_read_b128 v[196:199], v134 offset:53248
	ds_read_b128 v[200:203], v134 offset:54272
	ds_read_b128 v[204:207], v134 offset:55296
	ds_read_b128 v[208:211], v134 offset:56320
	s_mov_b32 m0, s80
	s_nop 0
	global_load_lds_dwordx4 v131, s[12:13]
	s_add_u32 s12, s48, 0x20080
	s_addc_u32 s13, s49, 0
	s_mov_b32 m0, s81
	s_nop 0
	global_load_lds_dwordx4 v131, s[12:13]
	s_add_u32 s12, s48, 0x40080
	s_addc_u32 s13, s49, 0
	s_mov_b32 m0, s85
	s_nop 0
	global_load_lds_dwordx4 v131, s[12:13]
	s_add_u32 s12, s48, 0x60080
	s_addc_u32 s13, s49, 0
	s_mov_b32 m0, s86
	s_nop 0
	global_load_lds_dwordx4 v131, s[12:13]
	s_mov_b32 m0, s82
	s_nop 0
	global_load_lds_dwordx4 v130, s[34:35]
	s_add_u32 s0, s0, 0x20080
	s_addc_u32 s1, s1, 0
	s_mov_b32 m0, s84
	s_nop 0
	global_load_lds_dwordx4 v130, s[0:1]
	s_waitcnt vmcnt(8)
	s_waitcnt lgkmcnt(0)
	s_barrier
	s_waitcnt lgkmcnt(7)
	v_mfma_f32_16x16x32_bf16 v[82:85], v[138:141], v[174:177], v[82:85]
	v_mfma_f32_16x16x32_bf16 v[74:77], v[146:149], v[174:177], v[74:77]
	s_waitcnt lgkmcnt(5)
	v_mfma_f32_16x16x32_bf16 v[98:101], v[138:141], v[188:191], v[98:101]
	v_mfma_f32_16x16x32_bf16 v[90:93], v[146:149], v[188:191], v[90:93]
	s_waitcnt lgkmcnt(3)
	v_mfma_f32_16x16x32_bf16 v[118:121], v[138:141], v[196:199], v[118:121]
	v_mfma_f32_16x16x32_bf16 v[114:117], v[146:149], v[196:199], v[114:117]
	s_waitcnt lgkmcnt(1)
	v_mfma_f32_16x16x32_bf16 v[126:129], v[138:141], v[204:207], v[126:129]
	v_mfma_f32_16x16x32_bf16 v[122:125], v[146:149], v[204:207], v[122:125]
	v_mfma_f32_16x16x32_bf16 v[82:85], v[142:145], v[184:187], v[82:85]
	v_mfma_f32_16x16x32_bf16 v[74:77], v[150:153], v[184:187], v[74:77]
	v_mfma_f32_16x16x32_bf16 v[98:101], v[142:145], v[192:195], v[98:101]
	v_mfma_f32_16x16x32_bf16 v[90:93], v[150:153], v[192:195], v[90:93]
	v_mfma_f32_16x16x32_bf16 v[118:121], v[142:145], v[200:203], v[118:121]
	v_mfma_f32_16x16x32_bf16 v[114:117], v[150:153], v[200:203], v[114:117]
	s_waitcnt lgkmcnt(0)
	v_mfma_f32_16x16x32_bf16 v[126:129], v[142:145], v[208:211], v[126:129]
	v_mfma_f32_16x16x32_bf16 v[122:125], v[150:153], v[208:211], v[122:125]
	v_mfma_f32_16x16x32_bf16 v[62:65], v[154:157], v[174:177], v[62:65]
	v_mfma_f32_16x16x32_bf16 v[58:61], v[166:169], v[174:177], v[58:61]
	v_mfma_f32_16x16x32_bf16 v[86:89], v[154:157], v[188:191], v[86:89]
	v_mfma_f32_16x16x32_bf16 v[78:81], v[166:169], v[188:191], v[78:81]
	v_mfma_f32_16x16x32_bf16 v[102:105], v[154:157], v[196:199], v[102:105]
	v_mfma_f32_16x16x32_bf16 v[94:97], v[166:169], v[196:199], v[94:97]
	v_mfma_f32_16x16x32_bf16 v[110:113], v[154:157], v[204:207], v[110:113]
	v_mfma_f32_16x16x32_bf16 v[106:109], v[166:169], v[204:207], v[106:109]
	v_mfma_f32_16x16x32_bf16 v[62:65], v[158:161], v[184:187], v[62:65]
	v_mfma_f32_16x16x32_bf16 v[58:61], v[170:173], v[184:187], v[58:61]
	v_mfma_f32_16x16x32_bf16 v[86:89], v[158:161], v[192:195], v[86:89]
	v_mfma_f32_16x16x32_bf16 v[78:81], v[170:173], v[192:195], v[78:81]
	v_mfma_f32_16x16x32_bf16 v[102:105], v[158:161], v[200:203], v[102:105]
	v_mfma_f32_16x16x32_bf16 v[94:97], v[170:173], v[200:203], v[94:97]
	v_mfma_f32_16x16x32_bf16 v[110:113], v[158:161], v[208:211], v[110:113]
	v_mfma_f32_16x16x32_bf16 v[106:109], v[170:173], v[208:211], v[106:109]
	s_barrier
	s_add_i32 s90, s90, 2
	s_add_u32 s46, s46, 0x100
	s_addc_u32 s47, s47, 0
	s_cmp_lt_u32 s90, 14
	s_cbranch_scc1 .LBB0_1317
	s_waitcnt vmcnt(0)
	s_cmpk_gt_u32 s65, 0xff
	s_cbranch_scc1 .LBB0_1320
	s_barrier

.LBB0_1424:
	v_add_u32_e32 v134, 0x10000, v139
	ds_read_b128 v[142:145], v134
	ds_read_b128 v[146:149], v134 offset:1024
	ds_read_b128 v[150:153], v134 offset:2048
	ds_read_b128 v[154:157], v134 offset:3072
	v_add_u32_e32 v134, 0x14000, v139
	ds_read_b128 v[158:161], v134
	ds_read_b128 v[162:165], v134 offset:1024
	ds_read_b128 v[166:169], v134 offset:2048
	ds_read_b128 v[170:173], v134 offset:3072
	s_add_u32 s0, s36, 0x100
	s_addc_u32 s1, s37, 0
	s_cmp_eq_u32 s66, 12
	s_cselect_b32 s34, s15, s0
	s_cselect_b32 s35, s14, s1
	s_cselect_b32 s40, s21, s64
	s_cselect_b32 s41, s11, s65
	s_add_u32 s38, s34, 0x80
	s_addc_u32 s39, s35, 0
	ds_read_b128 v[174:177], v140
	ds_read_b128 v[178:181], v140 offset:1024
	ds_read_b128 v[182:185], v140 offset:2048
	ds_read_b128 v[186:189], v140 offset:3072
	ds_read_b128 v[190:193], v140 offset:4096
	ds_read_b128 v[194:197], v140 offset:5120
	ds_read_b128 v[198:201], v140 offset:6144
	ds_read_b128 v[202:205], v140 offset:7168
	s_add_u32 s12, s36, 0x40080
	s_addc_u32 s13, s37, 0
	s_mov_b32 m0, s59
	s_nop 0
	global_load_lds_dwordx4 v1, s[12:13]
	s_add_u32 s12, s36, 0x60080
	s_addc_u32 s13, s37, 0
	s_add_i32 s36, s27, 0xe000
	s_mov_b32 m0, s36
	s_nop 0
	global_load_lds_dwordx4 v1, s[12:13]
	s_waitcnt vmcnt(8)
	s_waitcnt lgkmcnt(0)
	s_barrier
	s_waitcnt lgkmcnt(7)
	v_mfma_f32_16x16x32_bf16 v[122:125], v[142:145], v[174:177], v[122:125]
	v_mfma_f32_16x16x32_bf16 v[114:117], v[150:153], v[174:177], v[114:117]
	s_waitcnt lgkmcnt(5)
	v_mfma_f32_16x16x32_bf16 v[106:109], v[142:145], v[182:185], v[106:109]
	v_mfma_f32_16x16x32_bf16 v[98:101], v[150:153], v[182:185], v[98:101]
	s_waitcnt lgkmcnt(3)
	v_mfma_f32_16x16x32_bf16 v[90:93], v[142:145], v[190:193], v[90:93]
	v_mfma_f32_16x16x32_bf16 v[82:85], v[150:153], v[190:193], v[82:85]
	s_waitcnt lgkmcnt(1)
	v_mfma_f32_16x16x32_bf16 v[74:77], v[142:145], v[198:201], v[74:77]
	v_mfma_f32_16x16x32_bf16 v[66:69], v[150:153], v[198:201], v[66:69]
	v_mfma_f32_16x16x32_bf16 v[122:125], v[146:149], v[178:181], v[122:125]
	v_mfma_f32_16x16x32_bf16 v[114:117], v[154:157], v[178:181], v[114:117]
	v_mfma_f32_16x16x32_bf16 v[106:109], v[146:149], v[186:189], v[106:109]
	v_mfma_f32_16x16x32_bf16 v[98:101], v[154:157], v[186:189], v[98:101]
	v_mfma_f32_16x16x32_bf16 v[90:93], v[146:149], v[194:197], v[90:93]
	v_mfma_f32_16x16x32_bf16 v[82:85], v[154:157], v[194:197], v[82:85]
	s_waitcnt lgkmcnt(0)
	v_mfma_f32_16x16x32_bf16 v[74:77], v[146:149], v[202:205], v[74:77]
	v_mfma_f32_16x16x32_bf16 v[66:69], v[154:157], v[202:205], v[66:69]
	v_mfma_f32_16x16x32_bf16 v[126:129], v[158:161], v[174:177], v[126:129]
	v_mfma_f32_16x16x32_bf16 v[118:121], v[166:169], v[174:177], v[118:121]
	v_mfma_f32_16x16x32_bf16 v[110:113], v[158:161], v[182:185], v[110:113]
	v_mfma_f32_16x16x32_bf16 v[102:105], v[166:169], v[182:185], v[102:105]
	v_mfma_f32_16x16x32_bf16 v[94:97], v[158:161], v[190:193], v[94:97]
	v_mfma_f32_16x16x32_bf16 v[86:89], v[166:169], v[190:193], v[86:89]
	v_mfma_f32_16x16x32_bf16 v[78:81], v[158:161], v[198:201], v[78:81]
	v_mfma_f32_16x16x32_bf16 v[70:73], v[166:169], v[198:201], v[70:73]
	v_mfma_f32_16x16x32_bf16 v[126:129], v[162:165], v[178:181], v[126:129]
	v_mfma_f32_16x16x32_bf16 v[118:121], v[170:173], v[178:181], v[118:121]
	v_mfma_f32_16x16x32_bf16 v[110:113], v[162:165], v[186:189], v[110:113]
	v_mfma_f32_16x16x32_bf16 v[102:105], v[170:173], v[186:189], v[102:105]
	v_mfma_f32_16x16x32_bf16 v[94:97], v[162:165], v[194:197], v[94:97]
	v_mfma_f32_16x16x32_bf16 v[86:89], v[170:173], v[194:197], v[86:89]
	v_mfma_f32_16x16x32_bf16 v[78:81], v[162:165], v[202:205], v[78:81]
	v_mfma_f32_16x16x32_bf16 v[70:73], v[170:173], v[202:205], v[70:73]
	s_barrier
	ds_read_b128 v[174:177], v140 offset:16384
	ds_read_b128 v[178:181], v140 offset:17408
	ds_read_b128 v[182:185], v140 offset:18432
	ds_read_b128 v[186:189], v140 offset:19456
	ds_read_b128 v[190:193], v140 offset:20480
	ds_read_b128 v[194:197], v140 offset:21504
	ds_read_b128 v[198:201], v140 offset:22528
	ds_read_b128 v[202:205], v140 offset:23552
	s_mov_b32 m0, s46
	s_nop 0
	global_load_lds_dwordx4 v136, s[40:41]
	s_add_u32 s12, s40, 0x20000
	s_addc_u32 s13, s41, 0
	s_mov_b32 m0, s47
	s_nop 0
	global_load_lds_dwordx4 v136, s[12:13]
	s_add_u32 s12, s40, 0x40000
	s_addc_u32 s13, s41, 0
	s_mov_b32 m0, s48
	s_nop 0
	global_load_lds_dwordx4 v136, s[12:13]
	s_add_u32 s12, s40, 0x60000
	s_addc_u32 s13, s41, 0
	s_mov_b32 m0, s49
	s_nop 0
	global_load_lds_dwordx4 v136, s[12:13]
	s_mov_b32 m0, s27
	s_nop 0
	global_load_lds_dwordx4 v1, s[34:35]
	s_add_u32 s12, s34, 0x20000
	s_addc_u32 s13, s35, 0
	s_mov_b32 m0, s50
	s_nop 0
	global_load_lds_dwordx4 v1, s[12:13]
	s_waitcnt vmcnt(8)
	s_waitcnt lgkmcnt(0)
	s_barrier
	s_waitcnt lgkmcnt(7)
	v_mfma_f32_16x16x32_bf16 v[58:61], v[142:145], v[174:177], v[58:61]
	v_mfma_f32_16x16x32_bf16 v[50:53], v[150:153], v[174:177], v[50:53]
	s_waitcnt lgkmcnt(5)
	v_mfma_f32_16x16x32_bf16 v[42:45], v[142:145], v[182:185], v[42:45]
	v_mfma_f32_16x16x32_bf16 v[34:37], v[150:153], v[182:185], v[34:37]
	s_waitcnt lgkmcnt(3)
	v_mfma_f32_16x16x32_bf16 v[26:29], v[142:145], v[190:193], v[26:29]
	v_mfma_f32_16x16x32_bf16 v[18:21], v[150:153], v[190:193], v[18:21]
	s_waitcnt lgkmcnt(1)
	v_mfma_f32_16x16x32_bf16 v[10:13], v[142:145], v[198:201], v[10:13]
	v_mfma_f32_16x16x32_bf16 v[6:9], v[150:153], v[198:201], v[6:9]
	v_mfma_f32_16x16x32_bf16 v[58:61], v[146:149], v[178:181], v[58:61]
	v_mfma_f32_16x16x32_bf16 v[50:53], v[154:157], v[178:181], v[50:53]
	v_mfma_f32_16x16x32_bf16 v[42:45], v[146:149], v[186:189], v[42:45]
	v_mfma_f32_16x16x32_bf16 v[34:37], v[154:157], v[186:189], v[34:37]
	v_mfma_f32_16x16x32_bf16 v[26:29], v[146:149], v[194:197], v[26:29]
	v_mfma_f32_16x16x32_bf16 v[18:21], v[154:157], v[194:197], v[18:21]
	s_waitcnt lgkmcnt(0)
	v_mfma_f32_16x16x32_bf16 v[10:13], v[146:149], v[202:205], v[10:13]
	v_mfma_f32_16x16x32_bf16 v[6:9], v[154:157], v[202:205], v[6:9]
	v_mfma_f32_16x16x32_bf16 v[62:65], v[158:161], v[174:177], v[62:65]
	v_mfma_f32_16x16x32_bf16 v[54:57], v[166:169], v[174:177], v[54:57]
	v_mfma_f32_16x16x32_bf16 v[46:49], v[158:161], v[182:185], v[46:49]
	v_mfma_f32_16x16x32_bf16 v[38:41], v[166:169], v[182:185], v[38:41]
	v_mfma_f32_16x16x32_bf16 v[30:33], v[158:161], v[190:193], v[30:33]
	v_mfma_f32_16x16x32_bf16 v[22:25], v[166:169], v[190:193], v[22:25]
	v_mfma_f32_16x16x32_bf16 v[14:17], v[158:161], v[198:201], v[14:17]
	v_mfma_f32_16x16x32_bf16 v[2:5], v[166:169], v[198:201], v[2:5]
	v_mfma_f32_16x16x32_bf16 v[62:65], v[162:165], v[178:181], v[62:65]
	v_mfma_f32_16x16x32_bf16 v[54:57], v[170:173], v[178:181], v[54:57]
	v_mfma_f32_16x16x32_bf16 v[46:49], v[162:165], v[186:189], v[46:49]
	v_mfma_f32_16x16x32_bf16 v[38:41], v[170:173], v[186:189], v[38:41]
	v_mfma_f32_16x16x32_bf16 v[30:33], v[162:165], v[194:197], v[30:33]
	v_mfma_f32_16x16x32_bf16 v[22:25], v[170:173], v[194:197], v[22:25]
	v_mfma_f32_16x16x32_bf16 v[14:17], v[162:165], v[202:205], v[14:17]
	v_mfma_f32_16x16x32_bf16 v[2:5], v[170:173], v[202:205], v[2:5]
	s_barrier
	v_add_u32_e32 v134, 0x18000, v139
	ds_read_b128 v[142:145], v134
	ds_read_b128 v[146:149], v134 offset:1024
	ds_read_b128 v[150:153], v134 offset:2048
	ds_read_b128 v[154:157], v134 offset:3072
	v_add_u32_e32 v134, 0x1c000, v139
	ds_read_b128 v[158:161], v134
	ds_read_b128 v[162:165], v134 offset:1024
	ds_read_b128 v[166:169], v134 offset:2048
	ds_read_b128 v[170:173], v134 offset:3072
	ds_read_b128 v[174:177], v140 offset:32768
	ds_read_b128 v[178:181], v140 offset:33792
	ds_read_b128 v[182:185], v140 offset:34816
	ds_read_b128 v[186:189], v140 offset:35840
	ds_read_b128 v[190:193], v140 offset:36864
	ds_read_b128 v[194:197], v140 offset:37888
	ds_read_b128 v[198:201], v140 offset:38912
	ds_read_b128 v[202:205], v140 offset:39936
	s_add_u32 s12, s34, 0x40000
	s_addc_u32 s13, s35, 0
	s_mov_b32 m0, s51
	s_nop 0
	global_load_lds_dwordx4 v1, s[12:13]
	s_add_u32 s12, s34, 0x60000
	s_addc_u32 s13, s35, 0
	s_mov_b32 m0, s52
	s_nop 0
	global_load_lds_dwordx4 v1, s[12:13]
	s_waitcnt vmcnt(8)
	s_waitcnt lgkmcnt(0)
	s_barrier
	s_waitcnt lgkmcnt(7)
	v_mfma_f32_16x16x32_bf16 v[122:125], v[142:145], v[174:177], v[122:125]
	v_mfma_f32_16x16x32_bf16 v[114:117], v[150:153], v[174:177], v[114:117]
	s_waitcnt lgkmcnt(5)
	v_mfma_f32_16x16x32_bf16 v[106:109], v[142:145], v[182:185], v[106:109]
	v_mfma_f32_16x16x32_bf16 v[98:101], v[150:153], v[182:185], v[98:101]
	s_waitcnt lgkmcnt(3)
	v_mfma_f32_16x16x32_bf16 v[90:93], v[142:145], v[190:193], v[90:93]
	v_mfma_f32_16x16x32_bf16 v[82:85], v[150:153], v[190:193], v[82:85]
	s_waitcnt lgkmcnt(1)
	v_mfma_f32_16x16x32_bf16 v[74:77], v[142:145], v[198:201], v[74:77]
	v_mfma_f32_16x16x32_bf16 v[66:69], v[150:153], v[198:201], v[66:69]
	v_mfma_f32_16x16x32_bf16 v[122:125], v[146:149], v[178:181], v[122:125]
	v_mfma_f32_16x16x32_bf16 v[114:117], v[154:157], v[178:181], v[114:117]
	v_mfma_f32_16x16x32_bf16 v[106:109], v[146:149], v[186:189], v[106:109]
	v_mfma_f32_16x16x32_bf16 v[98:101], v[154:157], v[186:189], v[98:101]
	v_mfma_f32_16x16x32_bf16 v[90:93], v[146:149], v[194:197], v[90:93]
	v_mfma_f32_16x16x32_bf16 v[82:85], v[154:157], v[194:197], v[82:85]
	s_waitcnt lgkmcnt(0)
	v_mfma_f32_16x16x32_bf16 v[74:77], v[146:149], v[202:205], v[74:77]
	v_mfma_f32_16x16x32_bf16 v[66:69], v[154:157], v[202:205], v[66:69]
	v_mfma_f32_16x16x32_bf16 v[126:129], v[158:161], v[174:177], v[126:129]
	v_mfma_f32_16x16x32_bf16 v[118:121], v[166:169], v[174:177], v[118:121]
	v_mfma_f32_16x16x32_bf16 v[110:113], v[158:161], v[182:185], v[110:113]
	v_mfma_f32_16x16x32_bf16 v[102:105], v[166:169], v[182:185], v[102:105]
	v_mfma_f32_16x16x32_bf16 v[94:97], v[158:161], v[190:193], v[94:97]
	v_mfma_f32_16x16x32_bf16 v[86:89], v[166:169], v[190:193], v[86:89]
	v_mfma_f32_16x16x32_bf16 v[78:81], v[158:161], v[198:201], v[78:81]
	v_mfma_f32_16x16x32_bf16 v[70:73], v[166:169], v[198:201], v[70:73]
	v_mfma_f32_16x16x32_bf16 v[126:129], v[162:165], v[178:181], v[126:129]
	v_mfma_f32_16x16x32_bf16 v[118:121], v[170:173], v[178:181], v[118:121]
	v_mfma_f32_16x16x32_bf16 v[110:113], v[162:165], v[186:189], v[110:113]
	v_mfma_f32_16x16x32_bf16 v[102:105], v[170:173], v[186:189], v[102:105]
	v_mfma_f32_16x16x32_bf16 v[94:97], v[162:165], v[194:197], v[94:97]
	v_mfma_f32_16x16x32_bf16 v[86:89], v[170:173], v[194:197], v[86:89]
	v_mfma_f32_16x16x32_bf16 v[78:81], v[162:165], v[202:205], v[78:81]
	v_mfma_f32_16x16x32_bf16 v[70:73], v[170:173], v[202:205], v[70:73]
	s_barrier
	s_add_u32 s12, s40, 0x80
	s_addc_u32 s13, s41, 0
	ds_read_b128 v[174:177], v140 offset:49152
	ds_read_b128 v[178:181], v140 offset:50176
	ds_read_b128 v[182:185], v140 offset:51200
	ds_read_b128 v[186:189], v140 offset:52224
	ds_read_b128 v[190:193], v140 offset:53248
	ds_read_b128 v[194:197], v140 offset:54272
	ds_read_b128 v[198:201], v140 offset:55296
	ds_read_b128 v[202:205], v140 offset:56320
	s_mov_b32 m0, s53
	s_nop 0
	global_load_lds_dwordx4 v136, s[12:13]
	s_add_u32 s12, s40, 0x20080
	s_addc_u32 s13, s41, 0
	s_mov_b32 m0, s54
	s_nop 0
	global_load_lds_dwordx4 v136, s[12:13]
	s_add_u32 s12, s40, 0x40080
	s_addc_u32 s13, s41, 0
	s_mov_b32 m0, s57
	s_nop 0
	global_load_lds_dwordx4 v136, s[12:13]
	s_add_u32 s12, s40, 0x60080
	s_addc_u32 s13, s41, 0
	s_mov_b32 m0, s58
	s_nop 0
	global_load_lds_dwordx4 v136, s[12:13]
	s_mov_b32 m0, s55
	s_nop 0
	global_load_lds_dwordx4 v1, s[38:39]
	s_add_u32 s12, s34, 0x20080
	s_addc_u32 s13, s35, 0
	s_mov_b32 m0, s56
	s_nop 0
	global_load_lds_dwordx4 v1, s[12:13]
	s_waitcnt vmcnt(8)
	s_waitcnt lgkmcnt(0)
	s_barrier
	s_waitcnt lgkmcnt(7)
	v_mfma_f32_16x16x32_bf16 v[58:61], v[142:145], v[174:177], v[58:61]
	v_mfma_f32_16x16x32_bf16 v[50:53], v[150:153], v[174:177], v[50:53]
	s_waitcnt lgkmcnt(5)
	v_mfma_f32_16x16x32_bf16 v[42:45], v[142:145], v[182:185], v[42:45]
	v_mfma_f32_16x16x32_bf16 v[34:37], v[150:153], v[182:185], v[34:37]
	s_waitcnt lgkmcnt(3)
	v_mfma_f32_16x16x32_bf16 v[26:29], v[142:145], v[190:193], v[26:29]
	v_mfma_f32_16x16x32_bf16 v[18:21], v[150:153], v[190:193], v[18:21]
	s_waitcnt lgkmcnt(1)
	v_mfma_f32_16x16x32_bf16 v[10:13], v[142:145], v[198:201], v[10:13]
	v_mfma_f32_16x16x32_bf16 v[6:9], v[150:153], v[198:201], v[6:9]
	v_mfma_f32_16x16x32_bf16 v[58:61], v[146:149], v[178:181], v[58:61]
	v_mfma_f32_16x16x32_bf16 v[50:53], v[154:157], v[178:181], v[50:53]
	v_mfma_f32_16x16x32_bf16 v[42:45], v[146:149], v[186:189], v[42:45]
	v_mfma_f32_16x16x32_bf16 v[34:37], v[154:157], v[186:189], v[34:37]
	v_mfma_f32_16x16x32_bf16 v[26:29], v[146:149], v[194:197], v[26:29]
	v_mfma_f32_16x16x32_bf16 v[18:21], v[154:157], v[194:197], v[18:21]
	s_waitcnt lgkmcnt(0)
	v_mfma_f32_16x16x32_bf16 v[10:13], v[146:149], v[202:205], v[10:13]
	v_mfma_f32_16x16x32_bf16 v[6:9], v[154:157], v[202:205], v[6:9]
	v_mfma_f32_16x16x32_bf16 v[62:65], v[158:161], v[174:177], v[62:65]
	v_mfma_f32_16x16x32_bf16 v[54:57], v[166:169], v[174:177], v[54:57]
	v_mfma_f32_16x16x32_bf16 v[46:49], v[158:161], v[182:185], v[46:49]
	v_mfma_f32_16x16x32_bf16 v[38:41], v[166:169], v[182:185], v[38:41]
	v_mfma_f32_16x16x32_bf16 v[30:33], v[158:161], v[190:193], v[30:33]
	v_mfma_f32_16x16x32_bf16 v[22:25], v[166:169], v[190:193], v[22:25]
	v_mfma_f32_16x16x32_bf16 v[14:17], v[158:161], v[198:201], v[14:17]
	v_mfma_f32_16x16x32_bf16 v[2:5], v[166:169], v[198:201], v[2:5]
	v_mfma_f32_16x16x32_bf16 v[62:65], v[162:165], v[178:181], v[62:65]
	v_mfma_f32_16x16x32_bf16 v[54:57], v[170:173], v[178:181], v[54:57]
	v_mfma_f32_16x16x32_bf16 v[46:49], v[162:165], v[186:189], v[46:49]
	v_mfma_f32_16x16x32_bf16 v[38:41], v[170:173], v[186:189], v[38:41]
	v_mfma_f32_16x16x32_bf16 v[30:33], v[162:165], v[194:197], v[30:33]
	v_mfma_f32_16x16x32_bf16 v[22:25], v[170:173], v[194:197], v[22:25]
	v_mfma_f32_16x16x32_bf16 v[14:17], v[162:165], v[202:205], v[14:17]
	v_mfma_f32_16x16x32_bf16 v[2:5], v[170:173], v[202:205], v[2:5]
	s_barrier
	s_add_i32 s66, s66, 2
	s_add_u32 s64, s64, 0x100
	s_addc_u32 s65, s65, 0
	s_cmp_gt_u32 s66, 13
	s_mov_b64 s[36:37], s[0:1]
	s_cbranch_scc0 .LBB0_1424
	s_and_b64 vcc, exec, s[8:9]
	s_cbranch_vccz .LBB0_1427
	s_barrier
